# GEMM epilogue stores without sc0 sc1 (write-back, flushed by the grid barrier's buffer_wbl2)
# baseline (speedup 1.0000x reference)
.Lgm_f2_join:
	s_waitcnt lgkmcnt(13)
	v_mfma_f32_16x16x32_bf16 v[4:7], v[100:103], v[124:127], v[4:7]
	v_mfma_f32_16x16x32_bf16 v[20:23], v[104:107], v[124:127], v[20:23]
	v_mfma_f32_16x16x32_bf16 v[36:39], v[108:111], v[124:127], v[36:39]
	v_mfma_f32_16x16x32_bf16 v[52:55], v[112:115], v[124:127], v[52:55]
	v_mfma_f32_16x16x32_bf16 v[68:71], v[116:119], v[124:127], v[68:71]
	v_mfma_f32_16x16x32_bf16 v[84:87], v[120:123], v[124:127], v[84:87]
	s_waitcnt lgkmcnt(12)
	v_mfma_f32_16x16x32_bf16 v[8:11], v[100:103], v[128:131], v[8:11]
	v_mfma_f32_16x16x32_bf16 v[24:27], v[104:107], v[128:131], v[24:27]
	v_mfma_f32_16x16x32_bf16 v[40:43], v[108:111], v[128:131], v[40:43]
	v_mfma_f32_16x16x32_bf16 v[56:59], v[112:115], v[128:131], v[56:59]
	v_mfma_f32_16x16x32_bf16 v[72:75], v[116:119], v[128:131], v[72:75]
	v_mfma_f32_16x16x32_bf16 v[88:91], v[120:123], v[128:131], v[88:91]
	s_waitcnt lgkmcnt(11)
	v_mfma_f32_16x16x32_bf16 v[12:15], v[100:103], v[132:135], v[12:15]
	v_mfma_f32_16x16x32_bf16 v[28:31], v[104:107], v[132:135], v[28:31]
	v_mfma_f32_16x16x32_bf16 v[44:47], v[108:111], v[132:135], v[44:47]
	v_mfma_f32_16x16x32_bf16 v[60:63], v[112:115], v[132:135], v[60:63]
	v_mfma_f32_16x16x32_bf16 v[76:79], v[116:119], v[132:135], v[76:79]
	v_mfma_f32_16x16x32_bf16 v[92:95], v[120:123], v[132:135], v[92:95]
	s_waitcnt lgkmcnt(10)
	v_mfma_f32_16x16x32_bf16 v[16:19], v[100:103], v[136:139], v[16:19]
	v_mfma_f32_16x16x32_bf16 v[32:35], v[104:107], v[136:139], v[32:35]
	v_mfma_f32_16x16x32_bf16 v[48:51], v[108:111], v[136:139], v[48:51]
	v_mfma_f32_16x16x32_bf16 v[64:67], v[112:115], v[136:139], v[64:67]
	v_mfma_f32_16x16x32_bf16 v[80:83], v[116:119], v[136:139], v[80:83]
	v_mfma_f32_16x16x32_bf16 v[96:99], v[120:123], v[136:139], v[96:99]
	s_waitcnt lgkmcnt(0)
	s_add_u32 s34, s34, 1
	s_add_u32 s31, s31, 1
	s_cmp_lt_u32 s34, 64
	s_cbranch_scc1 .Lgm_f2_rot
	v_mfma_f32_16x16x32_bf16 v[4:7], v[140:143], v[164:167], v[4:7]
	v_mfma_f32_16x16x32_bf16 v[20:23], v[144:147], v[164:167], v[20:23]
	v_mfma_f32_16x16x32_bf16 v[36:39], v[148:151], v[164:167], v[36:39]
	v_mfma_f32_16x16x32_bf16 v[52:55], v[152:155], v[164:167], v[52:55]
	v_mfma_f32_16x16x32_bf16 v[68:71], v[156:159], v[164:167], v[68:71]
	v_mfma_f32_16x16x32_bf16 v[84:87], v[160:163], v[164:167], v[84:87]
	v_mfma_f32_16x16x32_bf16 v[8:11], v[140:143], v[168:171], v[8:11]
	v_mfma_f32_16x16x32_bf16 v[24:27], v[144:147], v[168:171], v[24:27]
	v_mfma_f32_16x16x32_bf16 v[40:43], v[148:151], v[168:171], v[40:43]
	v_mfma_f32_16x16x32_bf16 v[56:59], v[152:155], v[168:171], v[56:59]
	v_mfma_f32_16x16x32_bf16 v[72:75], v[156:159], v[168:171], v[72:75]
	v_mfma_f32_16x16x32_bf16 v[88:91], v[160:163], v[168:171], v[88:91]
	v_mfma_f32_16x16x32_bf16 v[12:15], v[140:143], v[172:175], v[12:15]
	v_mfma_f32_16x16x32_bf16 v[28:31], v[144:147], v[172:175], v[28:31]
	v_mfma_f32_16x16x32_bf16 v[44:47], v[148:151], v[172:175], v[44:47]
	v_mfma_f32_16x16x32_bf16 v[60:63], v[152:155], v[172:175], v[60:63]
	v_mfma_f32_16x16x32_bf16 v[76:79], v[156:159], v[172:175], v[76:79]
	v_mfma_f32_16x16x32_bf16 v[92:95], v[160:163], v[172:175], v[92:95]
	v_mfma_f32_16x16x32_bf16 v[16:19], v[140:143], v[176:179], v[16:19]
	v_mfma_f32_16x16x32_bf16 v[32:35], v[144:147], v[176:179], v[32:35]
	v_mfma_f32_16x16x32_bf16 v[48:51], v[148:151], v[176:179], v[48:51]
	v_mfma_f32_16x16x32_bf16 v[64:67], v[152:155], v[176:179], v[64:67]
	v_mfma_f32_16x16x32_bf16 v[80:83], v[156:159], v[176:179], v[80:83]
	v_mfma_f32_16x16x32_bf16 v[96:99], v[160:163], v[176:179], v[96:99]
	s_and_b32 s6, s35, 31
	s_lshr_b32 s7, s35, 5
	s_mul_i32 s6, s6, 192
	s_lshl_b32 s7, s7, 7
	s_nop 7
	s_mul_i32 s4, s6, 0x1000
	s_lshl_b32 s5, s7, 2
	s_add_u32 s4, s4, s5
	v_add_u32_e32 v197, s4, v205
	v_add_u32_e32 v192, s6, v190
	v_lshl_add_u32 v193, s7, 2, v191
	s_sub_i32 s4, s6, 0xc00
	s_max_i32 s4, s4, 0
	s_lshr_b32 s4, s4, 10
	s_add_i32 s5, s6, -2881
	s_max_i32 s5, s5, 0
	s_lshr_b32 s5, s5, 10
	s_movk_i32 s7, 0x1400
	s_cmp_eq_u32 s4, 0
	s_cselect_b32 s7, 0x1000, s7
	s_mul_i32 s4, s4, 0x6000
	s_mul_i32 s5, s5, 0x6000
	v_mov_b32_e32 v194, v197
	v_add_u32_e32 v195, 0, v192
	v_cmp_gt_u32_e32 vcc, 0x1000, v195
	v_mov_b32_e32 v0, s98
	v_mov_b32_e32 v1, s99
	v_mov_b32_e32 v3, s58
	v_cndmask_b32_e32 v0, v0, v3, vcc
	v_mov_b32_e32 v3, s59
	v_cndmask_b32_e32 v1, v1, v3, vcc
	v_add_co_u32_e32 v0, vcc, v0, v194
	s_nop 1
	v_addc_co_u32_e32 v1, vcc, 0, v1, vcc
	global_load_dwordx4 v[100:103], v[0:1], off
	v_add_u32_e32 v194, 0x4000, v194
	v_add_u32_e32 v195, 4, v192
	v_cmp_gt_u32_e32 vcc, 0x1000, v195
	v_mov_b32_e32 v0, s98
	v_mov_b32_e32 v1, s99
	v_mov_b32_e32 v3, s58
	v_cndmask_b32_e32 v0, v0, v3, vcc
	v_mov_b32_e32 v3, s59
	v_cndmask_b32_e32 v1, v1, v3, vcc
	v_add_co_u32_e32 v0, vcc, v0, v194
	s_nop 1
	v_addc_co_u32_e32 v1, vcc, 0, v1, vcc
	global_load_dwordx4 v[104:107], v[0:1], off
	v_add_u32_e32 v194, 0x4000, v194
	v_add_u32_e32 v195, 8, v192
	v_cmp_gt_u32_e32 vcc, 0x1000, v195
	v_mov_b32_e32 v0, s98
	v_mov_b32_e32 v1, s99
	v_mov_b32_e32 v3, s58
	v_cndmask_b32_e32 v0, v0, v3, vcc
	v_mov_b32_e32 v3, s59
	v_cndmask_b32_e32 v1, v1, v3, vcc
	v_add_co_u32_e32 v0, vcc, v0, v194
	s_nop 1
	v_addc_co_u32_e32 v1, vcc, 0, v1, vcc
	global_load_dwordx4 v[108:111], v[0:1], off
	v_add_u32_e32 v194, 0x4000, v194
	v_add_u32_e32 v195, 12, v192
	v_cmp_gt_u32_e32 vcc, 0x1000, v195
	v_mov_b32_e32 v0, s98
	v_mov_b32_e32 v1, s99
	v_mov_b32_e32 v3, s58
	v_cndmask_b32_e32 v0, v0, v3, vcc
	v_mov_b32_e32 v3, s59
	v_cndmask_b32_e32 v1, v1, v3, vcc
	v_add_co_u32_e32 v0, vcc, v0, v194
	s_nop 1
	v_addc_co_u32_e32 v1, vcc, 0, v1, vcc
	global_load_dwordx4 v[112:115], v[0:1], off
	v_add_u32_e32 v194, 0x4000, v194
	v_add_u32_e32 v195, 16, v192
	v_cmp_gt_u32_e32 vcc, 0x1000, v195
	v_mov_b32_e32 v0, s98
	v_mov_b32_e32 v1, s99
	v_mov_b32_e32 v3, s58
	v_cndmask_b32_e32 v0, v0, v3, vcc
	v_mov_b32_e32 v3, s59
	v_cndmask_b32_e32 v1, v1, v3, vcc
	v_add_co_u32_e32 v0, vcc, v0, v194
	s_nop 1
	v_addc_co_u32_e32 v1, vcc, 0, v1, vcc
	global_load_dwordx4 v[116:119], v[0:1], off
	v_add_u32_e32 v194, 0x4000, v194
	v_add_u32_e32 v195, 20, v192
	v_cmp_gt_u32_e32 vcc, 0x1000, v195
	v_mov_b32_e32 v0, s98
	v_mov_b32_e32 v1, s99
	v_mov_b32_e32 v3, s58
	v_cndmask_b32_e32 v0, v0, v3, vcc
	v_mov_b32_e32 v3, s59
	v_cndmask_b32_e32 v1, v1, v3, vcc
	v_add_co_u32_e32 v0, vcc, v0, v194
	s_nop 1
	v_addc_co_u32_e32 v1, vcc, 0, v1, vcc
	global_load_dwordx4 v[120:123], v[0:1], off
	v_add_u32_e32 v194, 0x4000, v194
	v_add_u32_e32 v195, 24, v192
	v_cmp_gt_u32_e32 vcc, 0x1000, v195
	v_mov_b32_e32 v0, s98
	v_mov_b32_e32 v1, s99
	v_mov_b32_e32 v3, s58
	v_cndmask_b32_e32 v0, v0, v3, vcc
	v_mov_b32_e32 v3, s59
	v_cndmask_b32_e32 v1, v1, v3, vcc
	v_add_co_u32_e32 v0, vcc, v0, v194
	s_nop 1
	v_addc_co_u32_e32 v1, vcc, 0, v1, vcc
	global_load_dwordx4 v[124:127], v[0:1], off
	v_add_u32_e32 v194, 0x4000, v194
	v_add_u32_e32 v195, 28, v192
	v_cmp_gt_u32_e32 vcc, 0x1000, v195
	v_mov_b32_e32 v0, s98
	v_mov_b32_e32 v1, s99
	v_mov_b32_e32 v3, s58
	v_cndmask_b32_e32 v0, v0, v3, vcc
	v_mov_b32_e32 v3, s59
	v_cndmask_b32_e32 v1, v1, v3, vcc
	v_add_co_u32_e32 v0, vcc, v0, v194
	s_nop 1
	v_addc_co_u32_e32 v1, vcc, 0, v1, vcc
	global_load_dwordx4 v[128:131], v[0:1], off
	v_add_u32_e32 v194, 0x4000, v194
	v_add_u32_e32 v195, 32, v192
	v_cmp_gt_u32_e32 vcc, 0x1000, v195
	v_mov_b32_e32 v0, s98
	v_mov_b32_e32 v1, s99
	v_mov_b32_e32 v3, s58
	v_cndmask_b32_e32 v0, v0, v3, vcc
	v_mov_b32_e32 v3, s59
	v_cndmask_b32_e32 v1, v1, v3, vcc
	v_add_co_u32_e32 v0, vcc, v0, v194
	s_nop 1
	v_addc_co_u32_e32 v1, vcc, 0, v1, vcc
	global_load_dwordx4 v[132:135], v[0:1], off
	v_add_u32_e32 v194, 0x4000, v194
	v_add_u32_e32 v195, 36, v192
	v_cmp_gt_u32_e32 vcc, 0x1000, v195
	v_mov_b32_e32 v0, s98
	v_mov_b32_e32 v1, s99
	v_mov_b32_e32 v3, s58
	v_cndmask_b32_e32 v0, v0, v3, vcc
	v_mov_b32_e32 v3, s59
	v_cndmask_b32_e32 v1, v1, v3, vcc
	v_add_co_u32_e32 v0, vcc, v0, v194
	s_nop 1
	v_addc_co_u32_e32 v1, vcc, 0, v1, vcc
	global_load_dwordx4 v[136:139], v[0:1], off
	v_add_u32_e32 v194, 0x4000, v194
	v_add_u32_e32 v195, 40, v192
	v_cmp_gt_u32_e32 vcc, 0x1000, v195
	v_mov_b32_e32 v0, s98
	v_mov_b32_e32 v1, s99
	v_mov_b32_e32 v3, s58
	v_cndmask_b32_e32 v0, v0, v3, vcc
	v_mov_b32_e32 v3, s59
	v_cndmask_b32_e32 v1, v1, v3, vcc
	v_add_co_u32_e32 v0, vcc, v0, v194
	s_nop 1
	v_addc_co_u32_e32 v1, vcc, 0, v1, vcc
	global_load_dwordx4 v[140:143], v[0:1], off
	v_add_u32_e32 v194, 0x4000, v194
	v_add_u32_e32 v195, 44, v192
	v_cmp_gt_u32_e32 vcc, 0x1000, v195
	v_mov_b32_e32 v0, s98
	v_mov_b32_e32 v1, s99
	v_mov_b32_e32 v3, s58
	v_cndmask_b32_e32 v0, v0, v3, vcc
	v_mov_b32_e32 v3, s59
	v_cndmask_b32_e32 v1, v1, v3, vcc
	v_add_co_u32_e32 v0, vcc, v0, v194
	s_nop 1
	v_addc_co_u32_e32 v1, vcc, 0, v1, vcc
	global_load_dwordx4 v[144:147], v[0:1], off
	v_add_u32_e32 v194, 0x4000, v194
	v_add_u32_e32 v195, s4, v193
	global_load_dwordx4 v[148:151], v195, s[100:101]
	v_add_u32_e32 v195, s5, v193
	global_load_dwordx4 v[152:155], v195, s[100:101]
	ds_write_b32 v203, v4 offset:0
	ds_write_b32 v203, v5 offset:272
	ds_write_b32 v203, v6 offset:544
	ds_write_b32 v203, v7 offset:816
	ds_write_b32 v203, v8 offset:64
	ds_write_b32 v203, v9 offset:336
	ds_write_b32 v203, v10 offset:608
	ds_write_b32 v203, v11 offset:880
	ds_write_b32 v203, v12 offset:128
	ds_write_b32 v203, v13 offset:400
	ds_write_b32 v203, v14 offset:672
	ds_write_b32 v203, v15 offset:944
	ds_write_b32 v203, v16 offset:192
	ds_write_b32 v203, v17 offset:464
	ds_write_b32 v203, v18 offset:736
	ds_write_b32 v203, v19 offset:1008
	s_waitcnt lgkmcnt(0)
	ds_read_b128 v[156:159], v204 offset:0
	ds_read_b128 v[160:163], v204 offset:1088
	ds_read_b128 v[164:167], v204 offset:2176
	ds_read_b128 v[168:171], v204 offset:3264
	s_waitcnt lgkmcnt(0)
	v_add_u32_e32 v195, 48, v192
	v_cmp_gt_u32_e32 vcc, 0x1000, v195
	v_mov_b32_e32 v0, s98
	v_mov_b32_e32 v1, s99
	v_mov_b32_e32 v3, s58
	v_cndmask_b32_e32 v0, v0, v3, vcc
	v_mov_b32_e32 v3, s59
	v_cndmask_b32_e32 v1, v1, v3, vcc
	v_add_co_u32_e32 v0, vcc, v0, v194
	s_nop 1
	v_addc_co_u32_e32 v1, vcc, 0, v1, vcc
	global_load_dwordx4 v[4:7], v[0:1], off
	v_add_u32_e32 v194, 0x4000, v194
	v_add_u32_e32 v195, 52, v192
	v_cmp_gt_u32_e32 vcc, 0x1000, v195
	v_mov_b32_e32 v0, s98
	v_mov_b32_e32 v1, s99
	v_mov_b32_e32 v3, s58
	v_cndmask_b32_e32 v0, v0, v3, vcc
	v_mov_b32_e32 v3, s59
	v_cndmask_b32_e32 v1, v1, v3, vcc
	v_add_co_u32_e32 v0, vcc, v0, v194
	s_nop 1
	v_addc_co_u32_e32 v1, vcc, 0, v1, vcc
	global_load_dwordx4 v[8:11], v[0:1], off
	v_add_u32_e32 v194, 0x4000, v194
	v_add_u32_e32 v195, 56, v192
	v_cmp_gt_u32_e32 vcc, 0x1000, v195
	v_mov_b32_e32 v0, s98
	v_mov_b32_e32 v1, s99
	v_mov_b32_e32 v3, s58
	v_cndmask_b32_e32 v0, v0, v3, vcc
	v_mov_b32_e32 v3, s59
	v_cndmask_b32_e32 v1, v1, v3, vcc
	v_add_co_u32_e32 v0, vcc, v0, v194
	s_nop 1
	v_addc_co_u32_e32 v1, vcc, 0, v1, vcc
	global_load_dwordx4 v[12:15], v[0:1], off
	v_add_u32_e32 v194, 0x4000, v194
	v_add_u32_e32 v195, 60, v192
	v_cmp_gt_u32_e32 vcc, 0x1000, v195
	v_mov_b32_e32 v0, s98
	v_mov_b32_e32 v1, s99
	v_mov_b32_e32 v3, s58
	v_cndmask_b32_e32 v0, v0, v3, vcc
	v_mov_b32_e32 v3, s59
	v_cndmask_b32_e32 v1, v1, v3, vcc
	v_add_co_u32_e32 v0, vcc, v0, v194
	s_nop 1
	v_addc_co_u32_e32 v1, vcc, 0, v1, vcc
	global_load_dwordx4 v[16:19], v[0:1], off
	v_add_u32_e32 v194, 0x4000, v194
	v_add_u32_e32 v195, 0, v192
	v_cmp_le_u32_e32 vcc, s7, v195
	s_waitcnt vmcnt(4)
	v_cndmask_b32_e32 v172, v148, v152, vcc
	v_cndmask_b32_e32 v173, v149, v153, vcc
	v_cndmask_b32_e32 v174, v150, v154, vcc
	v_cndmask_b32_e32 v175, v151, v155, vcc
	v_fmac_f32_e32 v100, v172, v156
	v_fmac_f32_e32 v101, v173, v157
	v_fmac_f32_e32 v102, v174, v158
	v_fmac_f32_e32 v103, v175, v159
	global_store_dwordx4 v197, v[100:103], s[56:57]
	v_add_u32_e32 v197, 0x4000, v197
	v_add_u32_e32 v195, 4, v192
	v_cmp_le_u32_e32 vcc, s7, v195
	s_waitcnt vmcnt(5)
	s_waitcnt lgkmcnt(2)
	v_cndmask_b32_e32 v172, v148, v152, vcc
	v_cndmask_b32_e32 v173, v149, v153, vcc
	v_cndmask_b32_e32 v174, v150, v154, vcc
	v_cndmask_b32_e32 v175, v151, v155, vcc
	v_fmac_f32_e32 v104, v172, v160
	v_fmac_f32_e32 v105, v173, v161
	v_fmac_f32_e32 v106, v174, v162
	v_fmac_f32_e32 v107, v175, v163
	global_store_dwordx4 v197, v[104:107], s[56:57]
	v_add_u32_e32 v197, 0x4000, v197
	v_add_u32_e32 v195, 8, v192
	v_cmp_le_u32_e32 vcc, s7, v195
	s_waitcnt vmcnt(6)
	s_waitcnt lgkmcnt(1)
	v_cndmask_b32_e32 v172, v148, v152, vcc
	v_cndmask_b32_e32 v173, v149, v153, vcc
	v_cndmask_b32_e32 v174, v150, v154, vcc
	v_cndmask_b32_e32 v175, v151, v155, vcc
	v_fmac_f32_e32 v108, v172, v164
	v_fmac_f32_e32 v109, v173, v165
	v_fmac_f32_e32 v110, v174, v166
	v_fmac_f32_e32 v111, v175, v167
	global_store_dwordx4 v197, v[108:111], s[56:57]
	v_add_u32_e32 v197, 0x4000, v197
	v_add_u32_e32 v195, 12, v192
	v_cmp_le_u32_e32 vcc, s7, v195
	s_waitcnt vmcnt(7)
	s_waitcnt lgkmcnt(0)
	v_cndmask_b32_e32 v172, v148, v152, vcc
	v_cndmask_b32_e32 v173, v149, v153, vcc
	v_cndmask_b32_e32 v174, v150, v154, vcc
	v_cndmask_b32_e32 v175, v151, v155, vcc
	v_fmac_f32_e32 v112, v172, v168
	v_fmac_f32_e32 v113, v173, v169
	v_fmac_f32_e32 v114, v174, v170
	v_fmac_f32_e32 v115, v175, v171
	global_store_dwordx4 v197, v[112:115], s[56:57]
	v_add_u32_e32 v197, 0x4000, v197
	ds_write_b32 v203, v20 offset:0
	ds_write_b32 v203, v21 offset:272
	ds_write_b32 v203, v22 offset:544
	ds_write_b32 v203, v23 offset:816
	ds_write_b32 v203, v24 offset:64
	ds_write_b32 v203, v25 offset:336
	ds_write_b32 v203, v26 offset:608
	ds_write_b32 v203, v27 offset:880
	ds_write_b32 v203, v28 offset:128
	ds_write_b32 v203, v29 offset:400
	ds_write_b32 v203, v30 offset:672
	ds_write_b32 v203, v31 offset:944
	ds_write_b32 v203, v32 offset:192
	ds_write_b32 v203, v33 offset:464
	ds_write_b32 v203, v34 offset:736
	ds_write_b32 v203, v35 offset:1008
	s_waitcnt lgkmcnt(0)
	ds_read_b128 v[156:159], v204 offset:0
	ds_read_b128 v[160:163], v204 offset:1088
	ds_read_b128 v[164:167], v204 offset:2176
	ds_read_b128 v[168:171], v204 offset:3264
	s_waitcnt lgkmcnt(0)
	v_add_u32_e32 v195, 64, v192
	v_cmp_gt_u32_e32 vcc, 0x1000, v195
	v_mov_b32_e32 v0, s98
	v_mov_b32_e32 v1, s99
	v_mov_b32_e32 v3, s58
	v_cndmask_b32_e32 v0, v0, v3, vcc
	v_mov_b32_e32 v3, s59
	v_cndmask_b32_e32 v1, v1, v3, vcc
	v_add_co_u32_e32 v0, vcc, v0, v194
	s_nop 1
	v_addc_co_u32_e32 v1, vcc, 0, v1, vcc
	global_load_dwordx4 v[20:23], v[0:1], off
	v_add_u32_e32 v194, 0x4000, v194
	v_add_u32_e32 v195, 68, v192
	v_cmp_gt_u32_e32 vcc, 0x1000, v195
	v_mov_b32_e32 v0, s98
	v_mov_b32_e32 v1, s99
	v_mov_b32_e32 v3, s58
	v_cndmask_b32_e32 v0, v0, v3, vcc
	v_mov_b32_e32 v3, s59
	v_cndmask_b32_e32 v1, v1, v3, vcc
	v_add_co_u32_e32 v0, vcc, v0, v194
	s_nop 1
	v_addc_co_u32_e32 v1, vcc, 0, v1, vcc
	global_load_dwordx4 v[24:27], v[0:1], off
	v_add_u32_e32 v194, 0x4000, v194
	v_add_u32_e32 v195, 72, v192
	v_cmp_gt_u32_e32 vcc, 0x1000, v195
	v_mov_b32_e32 v0, s98
	v_mov_b32_e32 v1, s99
	v_mov_b32_e32 v3, s58
	v_cndmask_b32_e32 v0, v0, v3, vcc
	v_mov_b32_e32 v3, s59
	v_cndmask_b32_e32 v1, v1, v3, vcc
	v_add_co_u32_e32 v0, vcc, v0, v194
	s_nop 1
	v_addc_co_u32_e32 v1, vcc, 0, v1, vcc
	global_load_dwordx4 v[28:31], v[0:1], off
	v_add_u32_e32 v194, 0x4000, v194
	v_add_u32_e32 v195, 76, v192
	v_cmp_gt_u32_e32 vcc, 0x1000, v195
	v_mov_b32_e32 v0, s98
	v_mov_b32_e32 v1, s99
	v_mov_b32_e32 v3, s58
	v_cndmask_b32_e32 v0, v0, v3, vcc
	v_mov_b32_e32 v3, s59
	v_cndmask_b32_e32 v1, v1, v3, vcc
	v_add_co_u32_e32 v0, vcc, v0, v194
	s_nop 1
	v_addc_co_u32_e32 v1, vcc, 0, v1, vcc
	global_load_dwordx4 v[32:35], v[0:1], off
	v_add_u32_e32 v194, 0x4000, v194
	v_add_u32_e32 v195, 16, v192
	v_cmp_le_u32_e32 vcc, s7, v195
	s_waitcnt vmcnt(12)
	v_cndmask_b32_e32 v172, v148, v152, vcc
	v_cndmask_b32_e32 v173, v149, v153, vcc
	v_cndmask_b32_e32 v174, v150, v154, vcc
	v_cndmask_b32_e32 v175, v151, v155, vcc
	v_fmac_f32_e32 v116, v172, v156
	v_fmac_f32_e32 v117, v173, v157
	v_fmac_f32_e32 v118, v174, v158
	v_fmac_f32_e32 v119, v175, v159
	global_store_dwordx4 v197, v[116:119], s[56:57]
	v_add_u32_e32 v197, 0x4000, v197
	v_add_u32_e32 v195, 20, v192
	v_cmp_le_u32_e32 vcc, s7, v195
	s_waitcnt vmcnt(13)
	s_waitcnt lgkmcnt(2)
	v_cndmask_b32_e32 v172, v148, v152, vcc
	v_cndmask_b32_e32 v173, v149, v153, vcc
	v_cndmask_b32_e32 v174, v150, v154, vcc
	v_cndmask_b32_e32 v175, v151, v155, vcc
	v_fmac_f32_e32 v120, v172, v160
	v_fmac_f32_e32 v121, v173, v161
	v_fmac_f32_e32 v122, v174, v162
	v_fmac_f32_e32 v123, v175, v163
	global_store_dwordx4 v197, v[120:123], s[56:57]
	v_add_u32_e32 v197, 0x4000, v197
	v_add_u32_e32 v195, 24, v192
	v_cmp_le_u32_e32 vcc, s7, v195
	s_waitcnt vmcnt(14)
	s_waitcnt lgkmcnt(1)
	v_cndmask_b32_e32 v172, v148, v152, vcc
	v_cndmask_b32_e32 v173, v149, v153, vcc
	v_cndmask_b32_e32 v174, v150, v154, vcc
	v_cndmask_b32_e32 v175, v151, v155, vcc
	v_fmac_f32_e32 v124, v172, v164
	v_fmac_f32_e32 v125, v173, v165
	v_fmac_f32_e32 v126, v174, v166
	v_fmac_f32_e32 v127, v175, v167
	global_store_dwordx4 v197, v[124:127], s[56:57]
	v_add_u32_e32 v197, 0x4000, v197
	v_add_u32_e32 v195, 28, v192
	v_cmp_le_u32_e32 vcc, s7, v195
	s_waitcnt vmcnt(15)
	s_waitcnt lgkmcnt(0)
	v_cndmask_b32_e32 v172, v148, v152, vcc
	v_cndmask_b32_e32 v173, v149, v153, vcc
	v_cndmask_b32_e32 v174, v150, v154, vcc
	v_cndmask_b32_e32 v175, v151, v155, vcc
	v_fmac_f32_e32 v128, v172, v168
	v_fmac_f32_e32 v129, v173, v169
	v_fmac_f32_e32 v130, v174, v170
	v_fmac_f32_e32 v131, v175, v171
	global_store_dwordx4 v197, v[128:131], s[56:57]
	v_add_u32_e32 v197, 0x4000, v197
	ds_write_b32 v203, v36 offset:0
	ds_write_b32 v203, v37 offset:272
	ds_write_b32 v203, v38 offset:544
	ds_write_b32 v203, v39 offset:816
	ds_write_b32 v203, v40 offset:64
	ds_write_b32 v203, v41 offset:336
	ds_write_b32 v203, v42 offset:608
	ds_write_b32 v203, v43 offset:880
	ds_write_b32 v203, v44 offset:128
	ds_write_b32 v203, v45 offset:400
	ds_write_b32 v203, v46 offset:672
	ds_write_b32 v203, v47 offset:944
	ds_write_b32 v203, v48 offset:192
	ds_write_b32 v203, v49 offset:464
	ds_write_b32 v203, v50 offset:736
	ds_write_b32 v203, v51 offset:1008
	s_waitcnt lgkmcnt(0)
	ds_read_b128 v[156:159], v204 offset:0
	ds_read_b128 v[160:163], v204 offset:1088
	ds_read_b128 v[164:167], v204 offset:2176
	ds_read_b128 v[168:171], v204 offset:3264
	s_waitcnt lgkmcnt(0)
	v_add_u32_e32 v195, 80, v192
	v_cmp_gt_u32_e32 vcc, 0x1000, v195
	v_mov_b32_e32 v0, s98
	v_mov_b32_e32 v1, s99
	v_mov_b32_e32 v3, s58
	v_cndmask_b32_e32 v0, v0, v3, vcc
	v_mov_b32_e32 v3, s59
	v_cndmask_b32_e32 v1, v1, v3, vcc
	v_add_co_u32_e32 v0, vcc, v0, v194
	s_nop 1
	v_addc_co_u32_e32 v1, vcc, 0, v1, vcc
	global_load_dwordx4 v[36:39], v[0:1], off
	v_add_u32_e32 v194, 0x4000, v194
	v_add_u32_e32 v195, 84, v192
	v_cmp_gt_u32_e32 vcc, 0x1000, v195
	v_mov_b32_e32 v0, s98
	v_mov_b32_e32 v1, s99
	v_mov_b32_e32 v3, s58
	v_cndmask_b32_e32 v0, v0, v3, vcc
	v_mov_b32_e32 v3, s59
	v_cndmask_b32_e32 v1, v1, v3, vcc
	v_add_co_u32_e32 v0, vcc, v0, v194
	s_nop 1
	v_addc_co_u32_e32 v1, vcc, 0, v1, vcc
	global_load_dwordx4 v[40:43], v[0:1], off
	v_add_u32_e32 v194, 0x4000, v194
	v_add_u32_e32 v195, 88, v192
	v_cmp_gt_u32_e32 vcc, 0x1000, v195
	v_mov_b32_e32 v0, s98
	v_mov_b32_e32 v1, s99
	v_mov_b32_e32 v3, s58
	v_cndmask_b32_e32 v0, v0, v3, vcc
	v_mov_b32_e32 v3, s59
	v_cndmask_b32_e32 v1, v1, v3, vcc
	v_add_co_u32_e32 v0, vcc, v0, v194
	s_nop 1
	v_addc_co_u32_e32 v1, vcc, 0, v1, vcc
	global_load_dwordx4 v[44:47], v[0:1], off
	v_add_u32_e32 v194, 0x4000, v194
	v_add_u32_e32 v195, 92, v192
	v_cmp_gt_u32_e32 vcc, 0x1000, v195
	v_mov_b32_e32 v0, s98
	v_mov_b32_e32 v1, s99
	v_mov_b32_e32 v3, s58
	v_cndmask_b32_e32 v0, v0, v3, vcc
	v_mov_b32_e32 v3, s59
	v_cndmask_b32_e32 v1, v1, v3, vcc
	v_add_co_u32_e32 v0, vcc, v0, v194
	s_nop 1
	v_addc_co_u32_e32 v1, vcc, 0, v1, vcc
	global_load_dwordx4 v[48:51], v[0:1], off
	v_add_u32_e32 v194, 0x4000, v194
	v_add_u32_e32 v195, 32, v192
	v_cmp_le_u32_e32 vcc, s7, v195
	s_waitcnt vmcnt(20)
	v_cndmask_b32_e32 v172, v148, v152, vcc
	v_cndmask_b32_e32 v173, v149, v153, vcc
	v_cndmask_b32_e32 v174, v150, v154, vcc
	v_cndmask_b32_e32 v175, v151, v155, vcc
	v_fmac_f32_e32 v132, v172, v156
	v_fmac_f32_e32 v133, v173, v157
	v_fmac_f32_e32 v134, v174, v158
	v_fmac_f32_e32 v135, v175, v159
	global_store_dwordx4 v197, v[132:135], s[56:57]
	v_add_u32_e32 v197, 0x4000, v197
	v_add_u32_e32 v195, 36, v192
	v_cmp_le_u32_e32 vcc, s7, v195
	s_waitcnt vmcnt(21)
	s_waitcnt lgkmcnt(2)
	v_cndmask_b32_e32 v172, v148, v152, vcc
	v_cndmask_b32_e32 v173, v149, v153, vcc
	v_cndmask_b32_e32 v174, v150, v154, vcc
	v_cndmask_b32_e32 v175, v151, v155, vcc
	v_fmac_f32_e32 v136, v172, v160
	v_fmac_f32_e32 v137, v173, v161
	v_fmac_f32_e32 v138, v174, v162
	v_fmac_f32_e32 v139, v175, v163
	global_store_dwordx4 v197, v[136:139], s[56:57]
	v_add_u32_e32 v197, 0x4000, v197
	v_add_u32_e32 v195, 40, v192
	v_cmp_le_u32_e32 vcc, s7, v195
	s_waitcnt vmcnt(22)
	s_waitcnt lgkmcnt(1)
	v_cndmask_b32_e32 v172, v148, v152, vcc
	v_cndmask_b32_e32 v173, v149, v153, vcc
	v_cndmask_b32_e32 v174, v150, v154, vcc
	v_cndmask_b32_e32 v175, v151, v155, vcc
	v_fmac_f32_e32 v140, v172, v164
	v_fmac_f32_e32 v141, v173, v165
	v_fmac_f32_e32 v142, v174, v166
	v_fmac_f32_e32 v143, v175, v167
	global_store_dwordx4 v197, v[140:143], s[56:57]
	v_add_u32_e32 v197, 0x4000, v197
	v_add_u32_e32 v195, 44, v192
	v_cmp_le_u32_e32 vcc, s7, v195
	s_waitcnt vmcnt(23)
	s_waitcnt lgkmcnt(0)
	v_cndmask_b32_e32 v172, v148, v152, vcc
	v_cndmask_b32_e32 v173, v149, v153, vcc
	v_cndmask_b32_e32 v174, v150, v154, vcc
	v_cndmask_b32_e32 v175, v151, v155, vcc
	v_fmac_f32_e32 v144, v172, v168
	v_fmac_f32_e32 v145, v173, v169
	v_fmac_f32_e32 v146, v174, v170
	v_fmac_f32_e32 v147, v175, v171
	global_store_dwordx4 v197, v[144:147], s[56:57]
	v_add_u32_e32 v197, 0x4000, v197
	ds_write_b32 v203, v52 offset:0
	ds_write_b32 v203, v53 offset:272
	ds_write_b32 v203, v54 offset:544
	ds_write_b32 v203, v55 offset:816
	ds_write_b32 v203, v56 offset:64
	ds_write_b32 v203, v57 offset:336
	ds_write_b32 v203, v58 offset:608
	ds_write_b32 v203, v59 offset:880
	ds_write_b32 v203, v60 offset:128
	ds_write_b32 v203, v61 offset:400
	ds_write_b32 v203, v62 offset:672
	ds_write_b32 v203, v63 offset:944
	ds_write_b32 v203, v64 offset:192
	ds_write_b32 v203, v65 offset:464
	ds_write_b32 v203, v66 offset:736
	ds_write_b32 v203, v67 offset:1008
	s_waitcnt lgkmcnt(0)
	ds_read_b128 v[156:159], v204 offset:0
	ds_read_b128 v[160:163], v204 offset:1088
	ds_read_b128 v[164:167], v204 offset:2176
	ds_read_b128 v[168:171], v204 offset:3264
	v_add_u32_e32 v195, 48, v192
	v_cmp_le_u32_e32 vcc, s7, v195
	s_waitcnt vmcnt(23)
	s_waitcnt lgkmcnt(3)
	v_cndmask_b32_e32 v172, v148, v152, vcc
	v_cndmask_b32_e32 v173, v149, v153, vcc
	v_cndmask_b32_e32 v174, v150, v154, vcc
	v_cndmask_b32_e32 v175, v151, v155, vcc
	v_fmac_f32_e32 v4, v172, v156
	v_fmac_f32_e32 v5, v173, v157
	v_fmac_f32_e32 v6, v174, v158
	v_fmac_f32_e32 v7, v175, v159
	global_store_dwordx4 v197, v[4:7], s[56:57]
	v_add_u32_e32 v197, 0x4000, v197
	v_add_u32_e32 v195, 52, v192
	v_cmp_le_u32_e32 vcc, s7, v195
	s_waitcnt vmcnt(23)
	s_waitcnt lgkmcnt(2)
	v_cndmask_b32_e32 v172, v148, v152, vcc
	v_cndmask_b32_e32 v173, v149, v153, vcc
	v_cndmask_b32_e32 v174, v150, v154, vcc
	v_cndmask_b32_e32 v175, v151, v155, vcc
	v_fmac_f32_e32 v8, v172, v160
	v_fmac_f32_e32 v9, v173, v161
	v_fmac_f32_e32 v10, v174, v162
	v_fmac_f32_e32 v11, v175, v163
	global_store_dwordx4 v197, v[8:11], s[56:57]
	v_add_u32_e32 v197, 0x4000, v197
	v_add_u32_e32 v195, 56, v192
	v_cmp_le_u32_e32 vcc, s7, v195
	s_waitcnt vmcnt(23)
	s_waitcnt lgkmcnt(1)
	v_cndmask_b32_e32 v172, v148, v152, vcc
	v_cndmask_b32_e32 v173, v149, v153, vcc
	v_cndmask_b32_e32 v174, v150, v154, vcc
	v_cndmask_b32_e32 v175, v151, v155, vcc
	v_fmac_f32_e32 v12, v172, v164
	v_fmac_f32_e32 v13, v173, v165
	v_fmac_f32_e32 v14, v174, v166
	v_fmac_f32_e32 v15, v175, v167
	global_store_dwordx4 v197, v[12:15], s[56:57]
	v_add_u32_e32 v197, 0x4000, v197
	v_add_u32_e32 v195, 60, v192
	v_cmp_le_u32_e32 vcc, s7, v195
	s_waitcnt vmcnt(23)
	s_waitcnt lgkmcnt(0)
	v_cndmask_b32_e32 v172, v148, v152, vcc
	v_cndmask_b32_e32 v173, v149, v153, vcc
	v_cndmask_b32_e32 v174, v150, v154, vcc
	v_cndmask_b32_e32 v175, v151, v155, vcc
	v_fmac_f32_e32 v16, v172, v168
	v_fmac_f32_e32 v17, v173, v169
	v_fmac_f32_e32 v18, v174, v170
	v_fmac_f32_e32 v19, v175, v171
	global_store_dwordx4 v197, v[16:19], s[56:57]
	v_add_u32_e32 v197, 0x4000, v197
	ds_write_b32 v203, v68 offset:0
	ds_write_b32 v203, v69 offset:272
	ds_write_b32 v203, v70 offset:544
	ds_write_b32 v203, v71 offset:816
	ds_write_b32 v203, v72 offset:64
	ds_write_b32 v203, v73 offset:336
	ds_write_b32 v203, v74 offset:608
	ds_write_b32 v203, v75 offset:880
	ds_write_b32 v203, v76 offset:128
	ds_write_b32 v203, v77 offset:400
	ds_write_b32 v203, v78 offset:672
	ds_write_b32 v203, v79 offset:944
	ds_write_b32 v203, v80 offset:192
	ds_write_b32 v203, v81 offset:464
	ds_write_b32 v203, v82 offset:736
	ds_write_b32 v203, v83 offset:1008
	s_waitcnt lgkmcnt(0)
	ds_read_b128 v[156:159], v204 offset:0
	ds_read_b128 v[160:163], v204 offset:1088
	ds_read_b128 v[164:167], v204 offset:2176
	ds_read_b128 v[168:171], v204 offset:3264
	v_add_u32_e32 v195, 64, v192
	v_cmp_le_u32_e32 vcc, s7, v195
	s_waitcnt vmcnt(19)
	s_waitcnt lgkmcnt(3)
	v_cndmask_b32_e32 v172, v148, v152, vcc
	v_cndmask_b32_e32 v173, v149, v153, vcc
	v_cndmask_b32_e32 v174, v150, v154, vcc
	v_cndmask_b32_e32 v175, v151, v155, vcc
	v_fmac_f32_e32 v20, v172, v156
	v_fmac_f32_e32 v21, v173, v157
	v_fmac_f32_e32 v22, v174, v158
	v_fmac_f32_e32 v23, v175, v159
	global_store_dwordx4 v197, v[20:23], s[56:57]
	v_add_u32_e32 v197, 0x4000, v197
	v_add_u32_e32 v195, 68, v192
	v_cmp_le_u32_e32 vcc, s7, v195
	s_waitcnt vmcnt(19)
	s_waitcnt lgkmcnt(2)
	v_cndmask_b32_e32 v172, v148, v152, vcc
	v_cndmask_b32_e32 v173, v149, v153, vcc
	v_cndmask_b32_e32 v174, v150, v154, vcc
	v_cndmask_b32_e32 v175, v151, v155, vcc
	v_fmac_f32_e32 v24, v172, v160
	v_fmac_f32_e32 v25, v173, v161
	v_fmac_f32_e32 v26, v174, v162
	v_fmac_f32_e32 v27, v175, v163
	global_store_dwordx4 v197, v[24:27], s[56:57]
	v_add_u32_e32 v197, 0x4000, v197
	v_add_u32_e32 v195, 72, v192
	v_cmp_le_u32_e32 vcc, s7, v195
	s_waitcnt vmcnt(19)
	s_waitcnt lgkmcnt(1)
	v_cndmask_b32_e32 v172, v148, v152, vcc
	v_cndmask_b32_e32 v173, v149, v153, vcc
	v_cndmask_b32_e32 v174, v150, v154, vcc
	v_cndmask_b32_e32 v175, v151, v155, vcc
	v_fmac_f32_e32 v28, v172, v164
	v_fmac_f32_e32 v29, v173, v165
	v_fmac_f32_e32 v30, v174, v166
	v_fmac_f32_e32 v31, v175, v167
	global_store_dwordx4 v197, v[28:31], s[56:57]
	v_add_u32_e32 v197, 0x4000, v197
	v_add_u32_e32 v195, 76, v192
	v_cmp_le_u32_e32 vcc, s7, v195
	s_waitcnt vmcnt(19)
	s_waitcnt lgkmcnt(0)
	v_cndmask_b32_e32 v172, v148, v152, vcc
	v_cndmask_b32_e32 v173, v149, v153, vcc
	v_cndmask_b32_e32 v174, v150, v154, vcc
	v_cndmask_b32_e32 v175, v151, v155, vcc
	v_fmac_f32_e32 v32, v172, v168
	v_fmac_f32_e32 v33, v173, v169
	v_fmac_f32_e32 v34, v174, v170
	v_fmac_f32_e32 v35, v175, v171
	global_store_dwordx4 v197, v[32:35], s[56:57]
	v_add_u32_e32 v197, 0x4000, v197
	ds_write_b32 v203, v84 offset:0
	ds_write_b32 v203, v85 offset:272
	ds_write_b32 v203, v86 offset:544
	ds_write_b32 v203, v87 offset:816
	ds_write_b32 v203, v88 offset:64
	ds_write_b32 v203, v89 offset:336
	ds_write_b32 v203, v90 offset:608
	ds_write_b32 v203, v91 offset:880
	ds_write_b32 v203, v92 offset:128
	ds_write_b32 v203, v93 offset:400
	ds_write_b32 v203, v94 offset:672
	ds_write_b32 v203, v95 offset:944
	ds_write_b32 v203, v96 offset:192
	ds_write_b32 v203, v97 offset:464
	ds_write_b32 v203, v98 offset:736
	ds_write_b32 v203, v99 offset:1008
	s_waitcnt lgkmcnt(0)
	ds_read_b128 v[156:159], v204 offset:0
	ds_read_b128 v[160:163], v204 offset:1088
	ds_read_b128 v[164:167], v204 offset:2176
	ds_read_b128 v[168:171], v204 offset:3264
	v_add_u32_e32 v195, 80, v192
	v_cmp_le_u32_e32 vcc, s7, v195
	s_waitcnt vmcnt(15)
	s_waitcnt lgkmcnt(3)
	v_cndmask_b32_e32 v172, v148, v152, vcc
	v_cndmask_b32_e32 v173, v149, v153, vcc
	v_cndmask_b32_e32 v174, v150, v154, vcc
	v_cndmask_b32_e32 v175, v151, v155, vcc
	v_fmac_f32_e32 v36, v172, v156
	v_fmac_f32_e32 v37, v173, v157
	v_fmac_f32_e32 v38, v174, v158
	v_fmac_f32_e32 v39, v175, v159
	global_store_dwordx4 v197, v[36:39], s[56:57]
	v_add_u32_e32 v197, 0x4000, v197
	v_add_u32_e32 v195, 84, v192
	v_cmp_le_u32_e32 vcc, s7, v195
	s_waitcnt vmcnt(15)
	s_waitcnt lgkmcnt(2)
	v_cndmask_b32_e32 v172, v148, v152, vcc
	v_cndmask_b32_e32 v173, v149, v153, vcc
	v_cndmask_b32_e32 v174, v150, v154, vcc
	v_cndmask_b32_e32 v175, v151, v155, vcc
	v_fmac_f32_e32 v40, v172, v160
	v_fmac_f32_e32 v41, v173, v161
	v_fmac_f32_e32 v42, v174, v162
	v_fmac_f32_e32 v43, v175, v163
	global_store_dwordx4 v197, v[40:43], s[56:57]
	v_add_u32_e32 v197, 0x4000, v197
	v_add_u32_e32 v195, 88, v192
	v_cmp_le_u32_e32 vcc, s7, v195
	s_waitcnt vmcnt(15)
	s_waitcnt lgkmcnt(1)
	v_cndmask_b32_e32 v172, v148, v152, vcc
	v_cndmask_b32_e32 v173, v149, v153, vcc
	v_cndmask_b32_e32 v174, v150, v154, vcc
	v_cndmask_b32_e32 v175, v151, v155, vcc
	v_fmac_f32_e32 v44, v172, v164
	v_fmac_f32_e32 v45, v173, v165
	v_fmac_f32_e32 v46, v174, v166
	v_fmac_f32_e32 v47, v175, v167
	global_store_dwordx4 v197, v[44:47], s[56:57]
	v_add_u32_e32 v197, 0x4000, v197
	v_add_u32_e32 v195, 92, v192
	v_cmp_le_u32_e32 vcc, s7, v195
	s_waitcnt vmcnt(15)
	s_waitcnt lgkmcnt(0)
	v_cndmask_b32_e32 v172, v148, v152, vcc
	v_cndmask_b32_e32 v173, v149, v153, vcc
	v_cndmask_b32_e32 v174, v150, v154, vcc
	v_cndmask_b32_e32 v175, v151, v155, vcc
	v_fmac_f32_e32 v48, v172, v168
	v_fmac_f32_e32 v49, v173, v169
	v_fmac_f32_e32 v50, v174, v170
	v_fmac_f32_e32 v51, v175, v171
	global_store_dwordx4 v197, v[48:51], s[56:57]
	v_add_u32_e32 v197, 0x4000, v197
	v_mov_b32_e32 v4, 0
	v_mov_b32_e32 v5, 0
	v_mov_b32_e32 v6, 0
	v_mov_b32_e32 v7, 0
	v_mov_b32_e32 v8, 0
	v_mov_b32_e32 v9, 0
	v_mov_b32_e32 v10, 0
	v_mov_b32_e32 v11, 0
	v_mov_b32_e32 v12, 0
	v_mov_b32_e32 v13, 0
	v_mov_b32_e32 v14, 0
	v_mov_b32_e32 v15, 0
	v_mov_b32_e32 v16, 0
	v_mov_b32_e32 v17, 0
	v_mov_b32_e32 v18, 0
	v_mov_b32_e32 v19, 0
	v_mov_b32_e32 v20, 0
	v_mov_b32_e32 v21, 0
	v_mov_b32_e32 v22, 0
	v_mov_b32_e32 v23, 0
	v_mov_b32_e32 v24, 0
	v_mov_b32_e32 v25, 0
	v_mov_b32_e32 v26, 0
	v_mov_b32_e32 v27, 0
	v_mov_b32_e32 v28, 0
	v_mov_b32_e32 v29, 0
	v_mov_b32_e32 v30, 0
	v_mov_b32_e32 v31, 0
	v_mov_b32_e32 v32, 0
	v_mov_b32_e32 v33, 0
	v_mov_b32_e32 v34, 0
	v_mov_b32_e32 v35, 0
	v_mov_b32_e32 v36, 0
	v_mov_b32_e32 v37, 0
	v_mov_b32_e32 v38, 0
	v_mov_b32_e32 v39, 0
	v_mov_b32_e32 v40, 0
	v_mov_b32_e32 v41, 0
	v_mov_b32_e32 v42, 0
	v_mov_b32_e32 v43, 0
	v_mov_b32_e32 v44, 0
	v_mov_b32_e32 v45, 0
	v_mov_b32_e32 v46, 0
	v_mov_b32_e32 v47, 0
	v_mov_b32_e32 v48, 0
	v_mov_b32_e32 v49, 0
	v_mov_b32_e32 v50, 0
	v_mov_b32_e32 v51, 0
	v_mov_b32_e32 v52, 0
	v_mov_b32_e32 v53, 0
	v_mov_b32_e32 v54, 0
	v_mov_b32_e32 v55, 0
	v_mov_b32_e32 v56, 0
	v_mov_b32_e32 v57, 0
	v_mov_b32_e32 v58, 0
	v_mov_b32_e32 v59, 0
	v_mov_b32_e32 v60, 0
	v_mov_b32_e32 v61, 0
	v_mov_b32_e32 v62, 0
	v_mov_b32_e32 v63, 0
	v_mov_b32_e32 v64, 0
	v_mov_b32_e32 v65, 0
	v_mov_b32_e32 v66, 0
	v_mov_b32_e32 v67, 0
	v_mov_b32_e32 v68, 0
	v_mov_b32_e32 v69, 0
	v_mov_b32_e32 v70, 0
	v_mov_b32_e32 v71, 0
	v_mov_b32_e32 v72, 0
	v_mov_b32_e32 v73, 0
	v_mov_b32_e32 v74, 0
	v_mov_b32_e32 v75, 0
	v_mov_b32_e32 v76, 0
	v_mov_b32_e32 v77, 0
	v_mov_b32_e32 v78, 0
	v_mov_b32_e32 v79, 0
	v_mov_b32_e32 v80, 0
	v_mov_b32_e32 v81, 0
	v_mov_b32_e32 v82, 0
	v_mov_b32_e32 v83, 0
	v_mov_b32_e32 v84, 0
	v_mov_b32_e32 v85, 0
	v_mov_b32_e32 v86, 0
	v_mov_b32_e32 v87, 0
	v_mov_b32_e32 v88, 0
	v_mov_b32_e32 v89, 0
	v_mov_b32_e32 v90, 0
	v_mov_b32_e32 v91, 0
	v_mov_b32_e32 v92, 0
	v_mov_b32_e32 v93, 0
	v_mov_b32_e32 v94, 0
	v_mov_b32_e32 v95, 0
	v_mov_b32_e32 v96, 0
	v_mov_b32_e32 v97, 0
	v_mov_b32_e32 v98, 0
	v_mov_b32_e32 v99, 0
	s_mov_b32 s34, 0
	s_add_u32 s35, s35, s52
	s_cmp_ge_u32 s31, s30
	s_cbranch_scc1 .Lgm_f2_exit

.Lgm_wo_join:
	s_waitcnt lgkmcnt(13)
	v_mfma_f32_16x16x32_bf16 v[4:7], v[100:103], v[124:127], v[4:7]
	v_mfma_f32_16x16x32_bf16 v[20:23], v[104:107], v[124:127], v[20:23]
	v_mfma_f32_16x16x32_bf16 v[36:39], v[108:111], v[124:127], v[36:39]
	v_mfma_f32_16x16x32_bf16 v[52:55], v[112:115], v[124:127], v[52:55]
	v_mfma_f32_16x16x32_bf16 v[68:71], v[116:119], v[124:127], v[68:71]
	v_mfma_f32_16x16x32_bf16 v[84:87], v[120:123], v[124:127], v[84:87]
	s_waitcnt lgkmcnt(12)
	v_mfma_f32_16x16x32_bf16 v[8:11], v[100:103], v[128:131], v[8:11]
	v_mfma_f32_16x16x32_bf16 v[24:27], v[104:107], v[128:131], v[24:27]
	v_mfma_f32_16x16x32_bf16 v[40:43], v[108:111], v[128:131], v[40:43]
	v_mfma_f32_16x16x32_bf16 v[56:59], v[112:115], v[128:131], v[56:59]
	v_mfma_f32_16x16x32_bf16 v[72:75], v[116:119], v[128:131], v[72:75]
	v_mfma_f32_16x16x32_bf16 v[88:91], v[120:123], v[128:131], v[88:91]
	s_waitcnt lgkmcnt(11)
	v_mfma_f32_16x16x32_bf16 v[12:15], v[100:103], v[132:135], v[12:15]
	v_mfma_f32_16x16x32_bf16 v[28:31], v[104:107], v[132:135], v[28:31]
	v_mfma_f32_16x16x32_bf16 v[44:47], v[108:111], v[132:135], v[44:47]
	v_mfma_f32_16x16x32_bf16 v[60:63], v[112:115], v[132:135], v[60:63]
	v_mfma_f32_16x16x32_bf16 v[76:79], v[116:119], v[132:135], v[76:79]
	v_mfma_f32_16x16x32_bf16 v[92:95], v[120:123], v[132:135], v[92:95]
	s_waitcnt lgkmcnt(10)
	v_mfma_f32_16x16x32_bf16 v[16:19], v[100:103], v[136:139], v[16:19]
	v_mfma_f32_16x16x32_bf16 v[32:35], v[104:107], v[136:139], v[32:35]
	v_mfma_f32_16x16x32_bf16 v[48:51], v[108:111], v[136:139], v[48:51]
	v_mfma_f32_16x16x32_bf16 v[64:67], v[112:115], v[136:139], v[64:67]
	v_mfma_f32_16x16x32_bf16 v[80:83], v[116:119], v[136:139], v[80:83]
	v_mfma_f32_16x16x32_bf16 v[96:99], v[120:123], v[136:139], v[96:99]
	s_waitcnt lgkmcnt(0)
	s_add_u32 s34, s34, 1
	s_add_u32 s31, s31, 1
	s_cmp_lt_u32 s34, 16
	s_cbranch_scc1 .Lgm_wo_rot
	v_mfma_f32_16x16x32_bf16 v[4:7], v[140:143], v[164:167], v[4:7]
	v_mfma_f32_16x16x32_bf16 v[20:23], v[144:147], v[164:167], v[20:23]
	v_mfma_f32_16x16x32_bf16 v[36:39], v[148:151], v[164:167], v[36:39]
	v_mfma_f32_16x16x32_bf16 v[52:55], v[152:155], v[164:167], v[52:55]
	v_mfma_f32_16x16x32_bf16 v[68:71], v[156:159], v[164:167], v[68:71]
	v_mfma_f32_16x16x32_bf16 v[84:87], v[160:163], v[164:167], v[84:87]
	v_mfma_f32_16x16x32_bf16 v[8:11], v[140:143], v[168:171], v[8:11]
	v_mfma_f32_16x16x32_bf16 v[24:27], v[144:147], v[168:171], v[24:27]
	v_mfma_f32_16x16x32_bf16 v[40:43], v[148:151], v[168:171], v[40:43]
	v_mfma_f32_16x16x32_bf16 v[56:59], v[152:155], v[168:171], v[56:59]
	v_mfma_f32_16x16x32_bf16 v[72:75], v[156:159], v[168:171], v[72:75]
	v_mfma_f32_16x16x32_bf16 v[88:91], v[160:163], v[168:171], v[88:91]
	v_mfma_f32_16x16x32_bf16 v[12:15], v[140:143], v[172:175], v[12:15]
	v_mfma_f32_16x16x32_bf16 v[28:31], v[144:147], v[172:175], v[28:31]
	v_mfma_f32_16x16x32_bf16 v[44:47], v[148:151], v[172:175], v[44:47]
	v_mfma_f32_16x16x32_bf16 v[60:63], v[152:155], v[172:175], v[60:63]
	v_mfma_f32_16x16x32_bf16 v[76:79], v[156:159], v[172:175], v[76:79]
	v_mfma_f32_16x16x32_bf16 v[92:95], v[160:163], v[172:175], v[92:95]
	v_mfma_f32_16x16x32_bf16 v[16:19], v[140:143], v[176:179], v[16:19]
	v_mfma_f32_16x16x32_bf16 v[32:35], v[144:147], v[176:179], v[32:35]
	v_mfma_f32_16x16x32_bf16 v[48:51], v[148:151], v[176:179], v[48:51]
	v_mfma_f32_16x16x32_bf16 v[64:67], v[152:155], v[176:179], v[64:67]
	v_mfma_f32_16x16x32_bf16 v[80:83], v[156:159], v[176:179], v[80:83]
	v_mfma_f32_16x16x32_bf16 v[96:99], v[160:163], v[176:179], v[96:99]
	s_and_b32 s6, s35, 31
	s_lshr_b32 s7, s35, 5
	s_mul_i32 s6, s6, 192
	s_lshl_b32 s7, s7, 7
	s_nop 7
	s_mul_i32 s4, s6, 0x1000
	s_lshl_b32 s5, s7, 2
	s_add_u32 s4, s4, s5
	v_add_u32_e32 v197, s4, v205
	v_add_u32_e32 v192, s6, v190
	v_lshl_add_u32 v193, s7, 2, v191
	s_sub_i32 s4, s6, 0xc00
	s_max_i32 s4, s4, 0
	s_lshr_b32 s4, s4, 10
	s_add_i32 s5, s6, -2881
	s_max_i32 s5, s5, 0
	s_lshr_b32 s5, s5, 10
	s_movk_i32 s7, 0x1400
	s_cmp_eq_u32 s4, 0
	s_cselect_b32 s7, 0x1000, s7
	s_mul_i32 s4, s4, 0x6000
	s_mul_i32 s5, s5, 0x6000
	v_mov_b32_e32 v194, v197
	v_add_u32_e32 v195, 0, v192
	v_cmp_gt_u32_e32 vcc, 0x1000, v195
	v_mov_b32_e32 v0, s98
	v_mov_b32_e32 v1, s99
	v_mov_b32_e32 v3, s58
	v_cndmask_b32_e32 v0, v0, v3, vcc
	v_mov_b32_e32 v3, s59
	v_cndmask_b32_e32 v1, v1, v3, vcc
	v_add_co_u32_e32 v0, vcc, v0, v194
	s_nop 1
	v_addc_co_u32_e32 v1, vcc, 0, v1, vcc
	global_load_dwordx4 v[100:103], v[0:1], off
	v_add_u32_e32 v194, 0x4000, v194
	v_add_u32_e32 v195, 4, v192
	v_cmp_gt_u32_e32 vcc, 0x1000, v195
	v_mov_b32_e32 v0, s98
	v_mov_b32_e32 v1, s99
	v_mov_b32_e32 v3, s58
	v_cndmask_b32_e32 v0, v0, v3, vcc
	v_mov_b32_e32 v3, s59
	v_cndmask_b32_e32 v1, v1, v3, vcc
	v_add_co_u32_e32 v0, vcc, v0, v194
	s_nop 1
	v_addc_co_u32_e32 v1, vcc, 0, v1, vcc
	global_load_dwordx4 v[104:107], v[0:1], off
	v_add_u32_e32 v194, 0x4000, v194
	v_add_u32_e32 v195, 8, v192
	v_cmp_gt_u32_e32 vcc, 0x1000, v195
	v_mov_b32_e32 v0, s98
	v_mov_b32_e32 v1, s99
	v_mov_b32_e32 v3, s58
	v_cndmask_b32_e32 v0, v0, v3, vcc
	v_mov_b32_e32 v3, s59
	v_cndmask_b32_e32 v1, v1, v3, vcc
	v_add_co_u32_e32 v0, vcc, v0, v194
	s_nop 1
	v_addc_co_u32_e32 v1, vcc, 0, v1, vcc
	global_load_dwordx4 v[108:111], v[0:1], off
	v_add_u32_e32 v194, 0x4000, v194
	v_add_u32_e32 v195, 12, v192
	v_cmp_gt_u32_e32 vcc, 0x1000, v195
	v_mov_b32_e32 v0, s98
	v_mov_b32_e32 v1, s99
	v_mov_b32_e32 v3, s58
	v_cndmask_b32_e32 v0, v0, v3, vcc
	v_mov_b32_e32 v3, s59
	v_cndmask_b32_e32 v1, v1, v3, vcc
	v_add_co_u32_e32 v0, vcc, v0, v194
	s_nop 1
	v_addc_co_u32_e32 v1, vcc, 0, v1, vcc
	global_load_dwordx4 v[112:115], v[0:1], off
	v_add_u32_e32 v194, 0x4000, v194
	v_add_u32_e32 v195, 16, v192
	v_cmp_gt_u32_e32 vcc, 0x1000, v195
	v_mov_b32_e32 v0, s98
	v_mov_b32_e32 v1, s99
	v_mov_b32_e32 v3, s58
	v_cndmask_b32_e32 v0, v0, v3, vcc
	v_mov_b32_e32 v3, s59
	v_cndmask_b32_e32 v1, v1, v3, vcc
	v_add_co_u32_e32 v0, vcc, v0, v194
	s_nop 1
	v_addc_co_u32_e32 v1, vcc, 0, v1, vcc
	global_load_dwordx4 v[116:119], v[0:1], off
	v_add_u32_e32 v194, 0x4000, v194
	v_add_u32_e32 v195, 20, v192
	v_cmp_gt_u32_e32 vcc, 0x1000, v195
	v_mov_b32_e32 v0, s98
	v_mov_b32_e32 v1, s99
	v_mov_b32_e32 v3, s58
	v_cndmask_b32_e32 v0, v0, v3, vcc
	v_mov_b32_e32 v3, s59
	v_cndmask_b32_e32 v1, v1, v3, vcc
	v_add_co_u32_e32 v0, vcc, v0, v194
	s_nop 1
	v_addc_co_u32_e32 v1, vcc, 0, v1, vcc
	global_load_dwordx4 v[120:123], v[0:1], off
	v_add_u32_e32 v194, 0x4000, v194
	v_add_u32_e32 v195, 24, v192
	v_cmp_gt_u32_e32 vcc, 0x1000, v195
	v_mov_b32_e32 v0, s98
	v_mov_b32_e32 v1, s99
	v_mov_b32_e32 v3, s58
	v_cndmask_b32_e32 v0, v0, v3, vcc
	v_mov_b32_e32 v3, s59
	v_cndmask_b32_e32 v1, v1, v3, vcc
	v_add_co_u32_e32 v0, vcc, v0, v194
	s_nop 1
	v_addc_co_u32_e32 v1, vcc, 0, v1, vcc
	global_load_dwordx4 v[124:127], v[0:1], off
	v_add_u32_e32 v194, 0x4000, v194
	v_add_u32_e32 v195, 28, v192
	v_cmp_gt_u32_e32 vcc, 0x1000, v195
	v_mov_b32_e32 v0, s98
	v_mov_b32_e32 v1, s99
	v_mov_b32_e32 v3, s58
	v_cndmask_b32_e32 v0, v0, v3, vcc
	v_mov_b32_e32 v3, s59
	v_cndmask_b32_e32 v1, v1, v3, vcc
	v_add_co_u32_e32 v0, vcc, v0, v194
	s_nop 1
	v_addc_co_u32_e32 v1, vcc, 0, v1, vcc
	global_load_dwordx4 v[128:131], v[0:1], off
	v_add_u32_e32 v194, 0x4000, v194
	v_add_u32_e32 v195, 32, v192
	v_cmp_gt_u32_e32 vcc, 0x1000, v195
	v_mov_b32_e32 v0, s98
	v_mov_b32_e32 v1, s99
	v_mov_b32_e32 v3, s58
	v_cndmask_b32_e32 v0, v0, v3, vcc
	v_mov_b32_e32 v3, s59
	v_cndmask_b32_e32 v1, v1, v3, vcc
	v_add_co_u32_e32 v0, vcc, v0, v194
	s_nop 1
	v_addc_co_u32_e32 v1, vcc, 0, v1, vcc
	global_load_dwordx4 v[132:135], v[0:1], off
	v_add_u32_e32 v194, 0x4000, v194
	v_add_u32_e32 v195, 36, v192
	v_cmp_gt_u32_e32 vcc, 0x1000, v195
	v_mov_b32_e32 v0, s98
	v_mov_b32_e32 v1, s99
	v_mov_b32_e32 v3, s58
	v_cndmask_b32_e32 v0, v0, v3, vcc
	v_mov_b32_e32 v3, s59
	v_cndmask_b32_e32 v1, v1, v3, vcc
	v_add_co_u32_e32 v0, vcc, v0, v194
	s_nop 1
	v_addc_co_u32_e32 v1, vcc, 0, v1, vcc
	global_load_dwordx4 v[136:139], v[0:1], off
	v_add_u32_e32 v194, 0x4000, v194
	v_add_u32_e32 v195, 40, v192
	v_cmp_gt_u32_e32 vcc, 0x1000, v195
	v_mov_b32_e32 v0, s98
	v_mov_b32_e32 v1, s99
	v_mov_b32_e32 v3, s58
	v_cndmask_b32_e32 v0, v0, v3, vcc
	v_mov_b32_e32 v3, s59
	v_cndmask_b32_e32 v1, v1, v3, vcc
	v_add_co_u32_e32 v0, vcc, v0, v194
	s_nop 1
	v_addc_co_u32_e32 v1, vcc, 0, v1, vcc
	global_load_dwordx4 v[140:143], v[0:1], off
	v_add_u32_e32 v194, 0x4000, v194
	v_add_u32_e32 v195, 44, v192
	v_cmp_gt_u32_e32 vcc, 0x1000, v195
	v_mov_b32_e32 v0, s98
	v_mov_b32_e32 v1, s99
	v_mov_b32_e32 v3, s58
	v_cndmask_b32_e32 v0, v0, v3, vcc
	v_mov_b32_e32 v3, s59
	v_cndmask_b32_e32 v1, v1, v3, vcc
	v_add_co_u32_e32 v0, vcc, v0, v194
	s_nop 1
	v_addc_co_u32_e32 v1, vcc, 0, v1, vcc
	global_load_dwordx4 v[144:147], v[0:1], off
	v_add_u32_e32 v194, 0x4000, v194
	v_add_u32_e32 v195, s4, v193
	global_load_dwordx4 v[148:151], v195, s[100:101]
	v_add_u32_e32 v195, s5, v193
	global_load_dwordx4 v[152:155], v195, s[100:101]
	ds_write_b32 v203, v4 offset:0
	ds_write_b32 v203, v5 offset:272
	ds_write_b32 v203, v6 offset:544
	ds_write_b32 v203, v7 offset:816
	ds_write_b32 v203, v8 offset:64
	ds_write_b32 v203, v9 offset:336
	ds_write_b32 v203, v10 offset:608
	ds_write_b32 v203, v11 offset:880
	ds_write_b32 v203, v12 offset:128
	ds_write_b32 v203, v13 offset:400
	ds_write_b32 v203, v14 offset:672
	ds_write_b32 v203, v15 offset:944
	ds_write_b32 v203, v16 offset:192
	ds_write_b32 v203, v17 offset:464
	ds_write_b32 v203, v18 offset:736
	ds_write_b32 v203, v19 offset:1008
	s_waitcnt lgkmcnt(0)
	ds_read_b128 v[156:159], v204 offset:0
	ds_read_b128 v[160:163], v204 offset:1088
	ds_read_b128 v[164:167], v204 offset:2176
	ds_read_b128 v[168:171], v204 offset:3264
	s_waitcnt lgkmcnt(0)
	v_add_u32_e32 v195, 48, v192
	v_cmp_gt_u32_e32 vcc, 0x1000, v195
	v_mov_b32_e32 v0, s98
	v_mov_b32_e32 v1, s99
	v_mov_b32_e32 v3, s58
	v_cndmask_b32_e32 v0, v0, v3, vcc
	v_mov_b32_e32 v3, s59
	v_cndmask_b32_e32 v1, v1, v3, vcc
	v_add_co_u32_e32 v0, vcc, v0, v194
	s_nop 1
	v_addc_co_u32_e32 v1, vcc, 0, v1, vcc
	global_load_dwordx4 v[4:7], v[0:1], off
	v_add_u32_e32 v194, 0x4000, v194
	v_add_u32_e32 v195, 52, v192
	v_cmp_gt_u32_e32 vcc, 0x1000, v195
	v_mov_b32_e32 v0, s98
	v_mov_b32_e32 v1, s99
	v_mov_b32_e32 v3, s58
	v_cndmask_b32_e32 v0, v0, v3, vcc
	v_mov_b32_e32 v3, s59
	v_cndmask_b32_e32 v1, v1, v3, vcc
	v_add_co_u32_e32 v0, vcc, v0, v194
	s_nop 1
	v_addc_co_u32_e32 v1, vcc, 0, v1, vcc
	global_load_dwordx4 v[8:11], v[0:1], off
	v_add_u32_e32 v194, 0x4000, v194
	v_add_u32_e32 v195, 56, v192
	v_cmp_gt_u32_e32 vcc, 0x1000, v195
	v_mov_b32_e32 v0, s98
	v_mov_b32_e32 v1, s99
	v_mov_b32_e32 v3, s58
	v_cndmask_b32_e32 v0, v0, v3, vcc
	v_mov_b32_e32 v3, s59
	v_cndmask_b32_e32 v1, v1, v3, vcc
	v_add_co_u32_e32 v0, vcc, v0, v194
	s_nop 1
	v_addc_co_u32_e32 v1, vcc, 0, v1, vcc
	global_load_dwordx4 v[12:15], v[0:1], off
	v_add_u32_e32 v194, 0x4000, v194
	v_add_u32_e32 v195, 60, v192
	v_cmp_gt_u32_e32 vcc, 0x1000, v195
	v_mov_b32_e32 v0, s98
	v_mov_b32_e32 v1, s99
	v_mov_b32_e32 v3, s58
	v_cndmask_b32_e32 v0, v0, v3, vcc
	v_mov_b32_e32 v3, s59
	v_cndmask_b32_e32 v1, v1, v3, vcc
	v_add_co_u32_e32 v0, vcc, v0, v194
	s_nop 1
	v_addc_co_u32_e32 v1, vcc, 0, v1, vcc
	global_load_dwordx4 v[16:19], v[0:1], off
	v_add_u32_e32 v194, 0x4000, v194
	v_add_u32_e32 v195, 0, v192
	v_cmp_le_u32_e32 vcc, s7, v195
	s_waitcnt vmcnt(4)
	v_cndmask_b32_e32 v172, v148, v152, vcc
	v_cndmask_b32_e32 v173, v149, v153, vcc
	v_cndmask_b32_e32 v174, v150, v154, vcc
	v_cndmask_b32_e32 v175, v151, v155, vcc
	v_fmac_f32_e32 v100, v172, v156
	v_fmac_f32_e32 v101, v173, v157
	v_fmac_f32_e32 v102, v174, v158
	v_fmac_f32_e32 v103, v175, v159
	global_store_dwordx4 v197, v[100:103], s[56:57]
	v_add_u32_e32 v197, 0x4000, v197
	v_add_u32_e32 v195, 4, v192
	v_cmp_le_u32_e32 vcc, s7, v195
	s_waitcnt vmcnt(5)
	s_waitcnt lgkmcnt(2)
	v_cndmask_b32_e32 v172, v148, v152, vcc
	v_cndmask_b32_e32 v173, v149, v153, vcc
	v_cndmask_b32_e32 v174, v150, v154, vcc
	v_cndmask_b32_e32 v175, v151, v155, vcc
	v_fmac_f32_e32 v104, v172, v160
	v_fmac_f32_e32 v105, v173, v161
	v_fmac_f32_e32 v106, v174, v162
	v_fmac_f32_e32 v107, v175, v163
	global_store_dwordx4 v197, v[104:107], s[56:57]
	v_add_u32_e32 v197, 0x4000, v197
	v_add_u32_e32 v195, 8, v192
	v_cmp_le_u32_e32 vcc, s7, v195
	s_waitcnt vmcnt(6)
	s_waitcnt lgkmcnt(1)
	v_cndmask_b32_e32 v172, v148, v152, vcc
	v_cndmask_b32_e32 v173, v149, v153, vcc
	v_cndmask_b32_e32 v174, v150, v154, vcc
	v_cndmask_b32_e32 v175, v151, v155, vcc
	v_fmac_f32_e32 v108, v172, v164
	v_fmac_f32_e32 v109, v173, v165
	v_fmac_f32_e32 v110, v174, v166
	v_fmac_f32_e32 v111, v175, v167
	global_store_dwordx4 v197, v[108:111], s[56:57]
	v_add_u32_e32 v197, 0x4000, v197
	v_add_u32_e32 v195, 12, v192
	v_cmp_le_u32_e32 vcc, s7, v195
	s_waitcnt vmcnt(7)
	s_waitcnt lgkmcnt(0)
	v_cndmask_b32_e32 v172, v148, v152, vcc
	v_cndmask_b32_e32 v173, v149, v153, vcc
	v_cndmask_b32_e32 v174, v150, v154, vcc
	v_cndmask_b32_e32 v175, v151, v155, vcc
	v_fmac_f32_e32 v112, v172, v168
	v_fmac_f32_e32 v113, v173, v169
	v_fmac_f32_e32 v114, v174, v170
	v_fmac_f32_e32 v115, v175, v171
	global_store_dwordx4 v197, v[112:115], s[56:57]
	v_add_u32_e32 v197, 0x4000, v197
	ds_write_b32 v203, v20 offset:0
	ds_write_b32 v203, v21 offset:272
	ds_write_b32 v203, v22 offset:544
	ds_write_b32 v203, v23 offset:816
	ds_write_b32 v203, v24 offset:64
	ds_write_b32 v203, v25 offset:336
	ds_write_b32 v203, v26 offset:608
	ds_write_b32 v203, v27 offset:880
	ds_write_b32 v203, v28 offset:128
	ds_write_b32 v203, v29 offset:400
	ds_write_b32 v203, v30 offset:672
	ds_write_b32 v203, v31 offset:944
	ds_write_b32 v203, v32 offset:192
	ds_write_b32 v203, v33 offset:464
	ds_write_b32 v203, v34 offset:736
	ds_write_b32 v203, v35 offset:1008
	s_waitcnt lgkmcnt(0)
	ds_read_b128 v[156:159], v204 offset:0
	ds_read_b128 v[160:163], v204 offset:1088
	ds_read_b128 v[164:167], v204 offset:2176
	ds_read_b128 v[168:171], v204 offset:3264
	s_waitcnt lgkmcnt(0)
	v_add_u32_e32 v195, 64, v192
	v_cmp_gt_u32_e32 vcc, 0x1000, v195
	v_mov_b32_e32 v0, s98
	v_mov_b32_e32 v1, s99
	v_mov_b32_e32 v3, s58
	v_cndmask_b32_e32 v0, v0, v3, vcc
	v_mov_b32_e32 v3, s59
	v_cndmask_b32_e32 v1, v1, v3, vcc
	v_add_co_u32_e32 v0, vcc, v0, v194
	s_nop 1
	v_addc_co_u32_e32 v1, vcc, 0, v1, vcc
	global_load_dwordx4 v[20:23], v[0:1], off
	v_add_u32_e32 v194, 0x4000, v194
	v_add_u32_e32 v195, 68, v192
	v_cmp_gt_u32_e32 vcc, 0x1000, v195
	v_mov_b32_e32 v0, s98
	v_mov_b32_e32 v1, s99
	v_mov_b32_e32 v3, s58
	v_cndmask_b32_e32 v0, v0, v3, vcc
	v_mov_b32_e32 v3, s59
	v_cndmask_b32_e32 v1, v1, v3, vcc
	v_add_co_u32_e32 v0, vcc, v0, v194
	s_nop 1
	v_addc_co_u32_e32 v1, vcc, 0, v1, vcc
	global_load_dwordx4 v[24:27], v[0:1], off
	v_add_u32_e32 v194, 0x4000, v194
	v_add_u32_e32 v195, 72, v192
	v_cmp_gt_u32_e32 vcc, 0x1000, v195
	v_mov_b32_e32 v0, s98
	v_mov_b32_e32 v1, s99
	v_mov_b32_e32 v3, s58
	v_cndmask_b32_e32 v0, v0, v3, vcc
	v_mov_b32_e32 v3, s59
	v_cndmask_b32_e32 v1, v1, v3, vcc
	v_add_co_u32_e32 v0, vcc, v0, v194
	s_nop 1
	v_addc_co_u32_e32 v1, vcc, 0, v1, vcc
	global_load_dwordx4 v[28:31], v[0:1], off
	v_add_u32_e32 v194, 0x4000, v194
	v_add_u32_e32 v195, 76, v192
	v_cmp_gt_u32_e32 vcc, 0x1000, v195
	v_mov_b32_e32 v0, s98
	v_mov_b32_e32 v1, s99
	v_mov_b32_e32 v3, s58
	v_cndmask_b32_e32 v0, v0, v3, vcc
	v_mov_b32_e32 v3, s59
	v_cndmask_b32_e32 v1, v1, v3, vcc
	v_add_co_u32_e32 v0, vcc, v0, v194
	s_nop 1
	v_addc_co_u32_e32 v1, vcc, 0, v1, vcc
	global_load_dwordx4 v[32:35], v[0:1], off
	v_add_u32_e32 v194, 0x4000, v194
	v_add_u32_e32 v195, 16, v192
	v_cmp_le_u32_e32 vcc, s7, v195
	s_waitcnt vmcnt(12)
	v_cndmask_b32_e32 v172, v148, v152, vcc
	v_cndmask_b32_e32 v173, v149, v153, vcc
	v_cndmask_b32_e32 v174, v150, v154, vcc
	v_cndmask_b32_e32 v175, v151, v155, vcc
	v_fmac_f32_e32 v116, v172, v156
	v_fmac_f32_e32 v117, v173, v157
	v_fmac_f32_e32 v118, v174, v158
	v_fmac_f32_e32 v119, v175, v159
	global_store_dwordx4 v197, v[116:119], s[56:57]
	v_add_u32_e32 v197, 0x4000, v197
	v_add_u32_e32 v195, 20, v192
	v_cmp_le_u32_e32 vcc, s7, v195
	s_waitcnt vmcnt(13)
	s_waitcnt lgkmcnt(2)
	v_cndmask_b32_e32 v172, v148, v152, vcc
	v_cndmask_b32_e32 v173, v149, v153, vcc
	v_cndmask_b32_e32 v174, v150, v154, vcc
	v_cndmask_b32_e32 v175, v151, v155, vcc
	v_fmac_f32_e32 v120, v172, v160
	v_fmac_f32_e32 v121, v173, v161
	v_fmac_f32_e32 v122, v174, v162
	v_fmac_f32_e32 v123, v175, v163
	global_store_dwordx4 v197, v[120:123], s[56:57]
	v_add_u32_e32 v197, 0x4000, v197
	v_add_u32_e32 v195, 24, v192
	v_cmp_le_u32_e32 vcc, s7, v195
	s_waitcnt vmcnt(14)
	s_waitcnt lgkmcnt(1)
	v_cndmask_b32_e32 v172, v148, v152, vcc
	v_cndmask_b32_e32 v173, v149, v153, vcc
	v_cndmask_b32_e32 v174, v150, v154, vcc
	v_cndmask_b32_e32 v175, v151, v155, vcc
	v_fmac_f32_e32 v124, v172, v164
	v_fmac_f32_e32 v125, v173, v165
	v_fmac_f32_e32 v126, v174, v166
	v_fmac_f32_e32 v127, v175, v167
	global_store_dwordx4 v197, v[124:127], s[56:57]
	v_add_u32_e32 v197, 0x4000, v197
	v_add_u32_e32 v195, 28, v192
	v_cmp_le_u32_e32 vcc, s7, v195
	s_waitcnt vmcnt(15)
	s_waitcnt lgkmcnt(0)
	v_cndmask_b32_e32 v172, v148, v152, vcc
	v_cndmask_b32_e32 v173, v149, v153, vcc
	v_cndmask_b32_e32 v174, v150, v154, vcc
	v_cndmask_b32_e32 v175, v151, v155, vcc
	v_fmac_f32_e32 v128, v172, v168
	v_fmac_f32_e32 v129, v173, v169
	v_fmac_f32_e32 v130, v174, v170
	v_fmac_f32_e32 v131, v175, v171
	global_store_dwordx4 v197, v[128:131], s[56:57]
	v_add_u32_e32 v197, 0x4000, v197
	ds_write_b32 v203, v36 offset:0
	ds_write_b32 v203, v37 offset:272
	ds_write_b32 v203, v38 offset:544
	ds_write_b32 v203, v39 offset:816
	ds_write_b32 v203, v40 offset:64
	ds_write_b32 v203, v41 offset:336
	ds_write_b32 v203, v42 offset:608
	ds_write_b32 v203, v43 offset:880
	ds_write_b32 v203, v44 offset:128
	ds_write_b32 v203, v45 offset:400
	ds_write_b32 v203, v46 offset:672
	ds_write_b32 v203, v47 offset:944
	ds_write_b32 v203, v48 offset:192
	ds_write_b32 v203, v49 offset:464
	ds_write_b32 v203, v50 offset:736
	ds_write_b32 v203, v51 offset:1008
	s_waitcnt lgkmcnt(0)
	ds_read_b128 v[156:159], v204 offset:0
	ds_read_b128 v[160:163], v204 offset:1088
	ds_read_b128 v[164:167], v204 offset:2176
	ds_read_b128 v[168:171], v204 offset:3264
	s_waitcnt lgkmcnt(0)
	v_add_u32_e32 v195, 80, v192
	v_cmp_gt_u32_e32 vcc, 0x1000, v195
	v_mov_b32_e32 v0, s98
	v_mov_b32_e32 v1, s99
	v_mov_b32_e32 v3, s58
	v_cndmask_b32_e32 v0, v0, v3, vcc
	v_mov_b32_e32 v3, s59
	v_cndmask_b32_e32 v1, v1, v3, vcc
	v_add_co_u32_e32 v0, vcc, v0, v194
	s_nop 1
	v_addc_co_u32_e32 v1, vcc, 0, v1, vcc
	global_load_dwordx4 v[36:39], v[0:1], off
	v_add_u32_e32 v194, 0x4000, v194
	v_add_u32_e32 v195, 84, v192
	v_cmp_gt_u32_e32 vcc, 0x1000, v195
	v_mov_b32_e32 v0, s98
	v_mov_b32_e32 v1, s99
	v_mov_b32_e32 v3, s58
	v_cndmask_b32_e32 v0, v0, v3, vcc
	v_mov_b32_e32 v3, s59
	v_cndmask_b32_e32 v1, v1, v3, vcc
	v_add_co_u32_e32 v0, vcc, v0, v194
	s_nop 1
	v_addc_co_u32_e32 v1, vcc, 0, v1, vcc
	global_load_dwordx4 v[40:43], v[0:1], off
	v_add_u32_e32 v194, 0x4000, v194
	v_add_u32_e32 v195, 88, v192
	v_cmp_gt_u32_e32 vcc, 0x1000, v195
	v_mov_b32_e32 v0, s98
	v_mov_b32_e32 v1, s99
	v_mov_b32_e32 v3, s58
	v_cndmask_b32_e32 v0, v0, v3, vcc
	v_mov_b32_e32 v3, s59
	v_cndmask_b32_e32 v1, v1, v3, vcc
	v_add_co_u32_e32 v0, vcc, v0, v194
	s_nop 1
	v_addc_co_u32_e32 v1, vcc, 0, v1, vcc
	global_load_dwordx4 v[44:47], v[0:1], off
	v_add_u32_e32 v194, 0x4000, v194
	v_add_u32_e32 v195, 92, v192
	v_cmp_gt_u32_e32 vcc, 0x1000, v195
	v_mov_b32_e32 v0, s98
	v_mov_b32_e32 v1, s99
	v_mov_b32_e32 v3, s58
	v_cndmask_b32_e32 v0, v0, v3, vcc
	v_mov_b32_e32 v3, s59
	v_cndmask_b32_e32 v1, v1, v3, vcc
	v_add_co_u32_e32 v0, vcc, v0, v194
	s_nop 1
	v_addc_co_u32_e32 v1, vcc, 0, v1, vcc
	global_load_dwordx4 v[48:51], v[0:1], off
	v_add_u32_e32 v194, 0x4000, v194
	v_add_u32_e32 v195, 32, v192
	v_cmp_le_u32_e32 vcc, s7, v195
	s_waitcnt vmcnt(20)
	v_cndmask_b32_e32 v172, v148, v152, vcc
	v_cndmask_b32_e32 v173, v149, v153, vcc
	v_cndmask_b32_e32 v174, v150, v154, vcc
	v_cndmask_b32_e32 v175, v151, v155, vcc
	v_fmac_f32_e32 v132, v172, v156
	v_fmac_f32_e32 v133, v173, v157
	v_fmac_f32_e32 v134, v174, v158
	v_fmac_f32_e32 v135, v175, v159
	global_store_dwordx4 v197, v[132:135], s[56:57]
	v_add_u32_e32 v197, 0x4000, v197
	v_add_u32_e32 v195, 36, v192
	v_cmp_le_u32_e32 vcc, s7, v195
	s_waitcnt vmcnt(21)
	s_waitcnt lgkmcnt(2)
	v_cndmask_b32_e32 v172, v148, v152, vcc
	v_cndmask_b32_e32 v173, v149, v153, vcc
	v_cndmask_b32_e32 v174, v150, v154, vcc
	v_cndmask_b32_e32 v175, v151, v155, vcc
	v_fmac_f32_e32 v136, v172, v160
	v_fmac_f32_e32 v137, v173, v161
	v_fmac_f32_e32 v138, v174, v162
	v_fmac_f32_e32 v139, v175, v163
	global_store_dwordx4 v197, v[136:139], s[56:57]
	v_add_u32_e32 v197, 0x4000, v197
	v_add_u32_e32 v195, 40, v192
	v_cmp_le_u32_e32 vcc, s7, v195
	s_waitcnt vmcnt(22)
	s_waitcnt lgkmcnt(1)
	v_cndmask_b32_e32 v172, v148, v152, vcc
	v_cndmask_b32_e32 v173, v149, v153, vcc
	v_cndmask_b32_e32 v174, v150, v154, vcc
	v_cndmask_b32_e32 v175, v151, v155, vcc
	v_fmac_f32_e32 v140, v172, v164
	v_fmac_f32_e32 v141, v173, v165
	v_fmac_f32_e32 v142, v174, v166
	v_fmac_f32_e32 v143, v175, v167
	global_store_dwordx4 v197, v[140:143], s[56:57]
	v_add_u32_e32 v197, 0x4000, v197
	v_add_u32_e32 v195, 44, v192
	v_cmp_le_u32_e32 vcc, s7, v195
	s_waitcnt vmcnt(23)
	s_waitcnt lgkmcnt(0)
	v_cndmask_b32_e32 v172, v148, v152, vcc
	v_cndmask_b32_e32 v173, v149, v153, vcc
	v_cndmask_b32_e32 v174, v150, v154, vcc
	v_cndmask_b32_e32 v175, v151, v155, vcc
	v_fmac_f32_e32 v144, v172, v168
	v_fmac_f32_e32 v145, v173, v169
	v_fmac_f32_e32 v146, v174, v170
	v_fmac_f32_e32 v147, v175, v171
	global_store_dwordx4 v197, v[144:147], s[56:57]
	v_add_u32_e32 v197, 0x4000, v197
	ds_write_b32 v203, v52 offset:0
	ds_write_b32 v203, v53 offset:272
	ds_write_b32 v203, v54 offset:544
	ds_write_b32 v203, v55 offset:816
	ds_write_b32 v203, v56 offset:64
	ds_write_b32 v203, v57 offset:336
	ds_write_b32 v203, v58 offset:608
	ds_write_b32 v203, v59 offset:880
	ds_write_b32 v203, v60 offset:128
	ds_write_b32 v203, v61 offset:400
	ds_write_b32 v203, v62 offset:672
	ds_write_b32 v203, v63 offset:944
	ds_write_b32 v203, v64 offset:192
	ds_write_b32 v203, v65 offset:464
	ds_write_b32 v203, v66 offset:736
	ds_write_b32 v203, v67 offset:1008
	s_waitcnt lgkmcnt(0)
	ds_read_b128 v[156:159], v204 offset:0
	ds_read_b128 v[160:163], v204 offset:1088
	ds_read_b128 v[164:167], v204 offset:2176
	ds_read_b128 v[168:171], v204 offset:3264
	v_add_u32_e32 v195, 48, v192
	v_cmp_le_u32_e32 vcc, s7, v195
	s_waitcnt vmcnt(23)
	s_waitcnt lgkmcnt(3)
	v_cndmask_b32_e32 v172, v148, v152, vcc
	v_cndmask_b32_e32 v173, v149, v153, vcc
	v_cndmask_b32_e32 v174, v150, v154, vcc
	v_cndmask_b32_e32 v175, v151, v155, vcc
	v_fmac_f32_e32 v4, v172, v156
	v_fmac_f32_e32 v5, v173, v157
	v_fmac_f32_e32 v6, v174, v158
	v_fmac_f32_e32 v7, v175, v159
	global_store_dwordx4 v197, v[4:7], s[56:57]
	v_add_u32_e32 v197, 0x4000, v197
	v_add_u32_e32 v195, 52, v192
	v_cmp_le_u32_e32 vcc, s7, v195
	s_waitcnt vmcnt(23)
	s_waitcnt lgkmcnt(2)
	v_cndmask_b32_e32 v172, v148, v152, vcc
	v_cndmask_b32_e32 v173, v149, v153, vcc
	v_cndmask_b32_e32 v174, v150, v154, vcc
	v_cndmask_b32_e32 v175, v151, v155, vcc
	v_fmac_f32_e32 v8, v172, v160
	v_fmac_f32_e32 v9, v173, v161
	v_fmac_f32_e32 v10, v174, v162
	v_fmac_f32_e32 v11, v175, v163
	global_store_dwordx4 v197, v[8:11], s[56:57]
	v_add_u32_e32 v197, 0x4000, v197
	v_add_u32_e32 v195, 56, v192
	v_cmp_le_u32_e32 vcc, s7, v195
	s_waitcnt vmcnt(23)
	s_waitcnt lgkmcnt(1)
	v_cndmask_b32_e32 v172, v148, v152, vcc
	v_cndmask_b32_e32 v173, v149, v153, vcc
	v_cndmask_b32_e32 v174, v150, v154, vcc
	v_cndmask_b32_e32 v175, v151, v155, vcc
	v_fmac_f32_e32 v12, v172, v164
	v_fmac_f32_e32 v13, v173, v165
	v_fmac_f32_e32 v14, v174, v166
	v_fmac_f32_e32 v15, v175, v167
	global_store_dwordx4 v197, v[12:15], s[56:57]
	v_add_u32_e32 v197, 0x4000, v197
	v_add_u32_e32 v195, 60, v192
	v_cmp_le_u32_e32 vcc, s7, v195
	s_waitcnt vmcnt(23)
	s_waitcnt lgkmcnt(0)
	v_cndmask_b32_e32 v172, v148, v152, vcc
	v_cndmask_b32_e32 v173, v149, v153, vcc
	v_cndmask_b32_e32 v174, v150, v154, vcc
	v_cndmask_b32_e32 v175, v151, v155, vcc
	v_fmac_f32_e32 v16, v172, v168
	v_fmac_f32_e32 v17, v173, v169
	v_fmac_f32_e32 v18, v174, v170
	v_fmac_f32_e32 v19, v175, v171
	global_store_dwordx4 v197, v[16:19], s[56:57]
	v_add_u32_e32 v197, 0x4000, v197
	ds_write_b32 v203, v68 offset:0
	ds_write_b32 v203, v69 offset:272
	ds_write_b32 v203, v70 offset:544
	ds_write_b32 v203, v71 offset:816
	ds_write_b32 v203, v72 offset:64
	ds_write_b32 v203, v73 offset:336
	ds_write_b32 v203, v74 offset:608
	ds_write_b32 v203, v75 offset:880
	ds_write_b32 v203, v76 offset:128
	ds_write_b32 v203, v77 offset:400
	ds_write_b32 v203, v78 offset:672
	ds_write_b32 v203, v79 offset:944
	ds_write_b32 v203, v80 offset:192
	ds_write_b32 v203, v81 offset:464
	ds_write_b32 v203, v82 offset:736
	ds_write_b32 v203, v83 offset:1008
	s_waitcnt lgkmcnt(0)
	ds_read_b128 v[156:159], v204 offset:0
	ds_read_b128 v[160:163], v204 offset:1088
	ds_read_b128 v[164:167], v204 offset:2176
	ds_read_b128 v[168:171], v204 offset:3264
	v_add_u32_e32 v195, 64, v192
	v_cmp_le_u32_e32 vcc, s7, v195
	s_waitcnt vmcnt(19)
	s_waitcnt lgkmcnt(3)
	v_cndmask_b32_e32 v172, v148, v152, vcc
	v_cndmask_b32_e32 v173, v149, v153, vcc
	v_cndmask_b32_e32 v174, v150, v154, vcc
	v_cndmask_b32_e32 v175, v151, v155, vcc
	v_fmac_f32_e32 v20, v172, v156
	v_fmac_f32_e32 v21, v173, v157
	v_fmac_f32_e32 v22, v174, v158
	v_fmac_f32_e32 v23, v175, v159
	global_store_dwordx4 v197, v[20:23], s[56:57]
	v_add_u32_e32 v197, 0x4000, v197
	v_add_u32_e32 v195, 68, v192
	v_cmp_le_u32_e32 vcc, s7, v195
	s_waitcnt vmcnt(19)
	s_waitcnt lgkmcnt(2)
	v_cndmask_b32_e32 v172, v148, v152, vcc
	v_cndmask_b32_e32 v173, v149, v153, vcc
	v_cndmask_b32_e32 v174, v150, v154, vcc
	v_cndmask_b32_e32 v175, v151, v155, vcc
	v_fmac_f32_e32 v24, v172, v160
	v_fmac_f32_e32 v25, v173, v161
	v_fmac_f32_e32 v26, v174, v162
	v_fmac_f32_e32 v27, v175, v163
	global_store_dwordx4 v197, v[24:27], s[56:57]
	v_add_u32_e32 v197, 0x4000, v197
	v_add_u32_e32 v195, 72, v192
	v_cmp_le_u32_e32 vcc, s7, v195
	s_waitcnt vmcnt(19)
	s_waitcnt lgkmcnt(1)
	v_cndmask_b32_e32 v172, v148, v152, vcc
	v_cndmask_b32_e32 v173, v149, v153, vcc
	v_cndmask_b32_e32 v174, v150, v154, vcc
	v_cndmask_b32_e32 v175, v151, v155, vcc
	v_fmac_f32_e32 v28, v172, v164
	v_fmac_f32_e32 v29, v173, v165
	v_fmac_f32_e32 v30, v174, v166
	v_fmac_f32_e32 v31, v175, v167
	global_store_dwordx4 v197, v[28:31], s[56:57]
	v_add_u32_e32 v197, 0x4000, v197
	v_add_u32_e32 v195, 76, v192
	v_cmp_le_u32_e32 vcc, s7, v195
	s_waitcnt vmcnt(19)
	s_waitcnt lgkmcnt(0)
	v_cndmask_b32_e32 v172, v148, v152, vcc
	v_cndmask_b32_e32 v173, v149, v153, vcc
	v_cndmask_b32_e32 v174, v150, v154, vcc
	v_cndmask_b32_e32 v175, v151, v155, vcc
	v_fmac_f32_e32 v32, v172, v168
	v_fmac_f32_e32 v33, v173, v169
	v_fmac_f32_e32 v34, v174, v170
	v_fmac_f32_e32 v35, v175, v171
	global_store_dwordx4 v197, v[32:35], s[56:57]
	v_add_u32_e32 v197, 0x4000, v197
	ds_write_b32 v203, v84 offset:0
	ds_write_b32 v203, v85 offset:272
	ds_write_b32 v203, v86 offset:544
	ds_write_b32 v203, v87 offset:816
	ds_write_b32 v203, v88 offset:64
	ds_write_b32 v203, v89 offset:336
	ds_write_b32 v203, v90 offset:608
	ds_write_b32 v203, v91 offset:880
	ds_write_b32 v203, v92 offset:128
	ds_write_b32 v203, v93 offset:400
	ds_write_b32 v203, v94 offset:672
	ds_write_b32 v203, v95 offset:944
	ds_write_b32 v203, v96 offset:192
	ds_write_b32 v203, v97 offset:464
	ds_write_b32 v203, v98 offset:736
	ds_write_b32 v203, v99 offset:1008
	s_waitcnt lgkmcnt(0)
	ds_read_b128 v[156:159], v204 offset:0
	ds_read_b128 v[160:163], v204 offset:1088
	ds_read_b128 v[164:167], v204 offset:2176
	ds_read_b128 v[168:171], v204 offset:3264
	v_add_u32_e32 v195, 80, v192
	v_cmp_le_u32_e32 vcc, s7, v195
	s_waitcnt vmcnt(15)
	s_waitcnt lgkmcnt(3)
	v_cndmask_b32_e32 v172, v148, v152, vcc
	v_cndmask_b32_e32 v173, v149, v153, vcc
	v_cndmask_b32_e32 v174, v150, v154, vcc
	v_cndmask_b32_e32 v175, v151, v155, vcc
	v_fmac_f32_e32 v36, v172, v156
	v_fmac_f32_e32 v37, v173, v157
	v_fmac_f32_e32 v38, v174, v158
	v_fmac_f32_e32 v39, v175, v159
	global_store_dwordx4 v197, v[36:39], s[56:57]
	v_add_u32_e32 v197, 0x4000, v197
	v_add_u32_e32 v195, 84, v192
	v_cmp_le_u32_e32 vcc, s7, v195
	s_waitcnt vmcnt(15)
	s_waitcnt lgkmcnt(2)
	v_cndmask_b32_e32 v172, v148, v152, vcc
	v_cndmask_b32_e32 v173, v149, v153, vcc
	v_cndmask_b32_e32 v174, v150, v154, vcc
	v_cndmask_b32_e32 v175, v151, v155, vcc
	v_fmac_f32_e32 v40, v172, v160
	v_fmac_f32_e32 v41, v173, v161
	v_fmac_f32_e32 v42, v174, v162
	v_fmac_f32_e32 v43, v175, v163
	global_store_dwordx4 v197, v[40:43], s[56:57]
	v_add_u32_e32 v197, 0x4000, v197
	v_add_u32_e32 v195, 88, v192
	v_cmp_le_u32_e32 vcc, s7, v195
	s_waitcnt vmcnt(15)
	s_waitcnt lgkmcnt(1)
	v_cndmask_b32_e32 v172, v148, v152, vcc
	v_cndmask_b32_e32 v173, v149, v153, vcc
	v_cndmask_b32_e32 v174, v150, v154, vcc
	v_cndmask_b32_e32 v175, v151, v155, vcc
	v_fmac_f32_e32 v44, v172, v164
	v_fmac_f32_e32 v45, v173, v165
	v_fmac_f32_e32 v46, v174, v166
	v_fmac_f32_e32 v47, v175, v167
	global_store_dwordx4 v197, v[44:47], s[56:57]
	v_add_u32_e32 v197, 0x4000, v197
	v_add_u32_e32 v195, 92, v192
	v_cmp_le_u32_e32 vcc, s7, v195
	s_waitcnt vmcnt(15)
	s_waitcnt lgkmcnt(0)
	v_cndmask_b32_e32 v172, v148, v152, vcc
	v_cndmask_b32_e32 v173, v149, v153, vcc
	v_cndmask_b32_e32 v174, v150, v154, vcc
	v_cndmask_b32_e32 v175, v151, v155, vcc
	v_fmac_f32_e32 v48, v172, v168
	v_fmac_f32_e32 v49, v173, v169
	v_fmac_f32_e32 v50, v174, v170
	v_fmac_f32_e32 v51, v175, v171
	global_store_dwordx4 v197, v[48:51], s[56:57]
	v_add_u32_e32 v197, 0x4000, v197
	v_mov_b32_e32 v4, 0
	v_mov_b32_e32 v5, 0
	v_mov_b32_e32 v6, 0
	v_mov_b32_e32 v7, 0
	v_mov_b32_e32 v8, 0
	v_mov_b32_e32 v9, 0
	v_mov_b32_e32 v10, 0
	v_mov_b32_e32 v11, 0
	v_mov_b32_e32 v12, 0
	v_mov_b32_e32 v13, 0
	v_mov_b32_e32 v14, 0
	v_mov_b32_e32 v15, 0
	v_mov_b32_e32 v16, 0
	v_mov_b32_e32 v17, 0
	v_mov_b32_e32 v18, 0
	v_mov_b32_e32 v19, 0
	v_mov_b32_e32 v20, 0
	v_mov_b32_e32 v21, 0
	v_mov_b32_e32 v22, 0
	v_mov_b32_e32 v23, 0
	v_mov_b32_e32 v24, 0
	v_mov_b32_e32 v25, 0
	v_mov_b32_e32 v26, 0
	v_mov_b32_e32 v27, 0
	v_mov_b32_e32 v28, 0
	v_mov_b32_e32 v29, 0
	v_mov_b32_e32 v30, 0
	v_mov_b32_e32 v31, 0
	v_mov_b32_e32 v32, 0
	v_mov_b32_e32 v33, 0
	v_mov_b32_e32 v34, 0
	v_mov_b32_e32 v35, 0
	v_mov_b32_e32 v36, 0
	v_mov_b32_e32 v37, 0
	v_mov_b32_e32 v38, 0
	v_mov_b32_e32 v39, 0
	v_mov_b32_e32 v40, 0
	v_mov_b32_e32 v41, 0
	v_mov_b32_e32 v42, 0
	v_mov_b32_e32 v43, 0
	v_mov_b32_e32 v44, 0
	v_mov_b32_e32 v45, 0
	v_mov_b32_e32 v46, 0
	v_mov_b32_e32 v47, 0
	v_mov_b32_e32 v48, 0
	v_mov_b32_e32 v49, 0
	v_mov_b32_e32 v50, 0
	v_mov_b32_e32 v51, 0
	v_mov_b32_e32 v52, 0
	v_mov_b32_e32 v53, 0
	v_mov_b32_e32 v54, 0
	v_mov_b32_e32 v55, 0
	v_mov_b32_e32 v56, 0
	v_mov_b32_e32 v57, 0
	v_mov_b32_e32 v58, 0
	v_mov_b32_e32 v59, 0
	v_mov_b32_e32 v60, 0
	v_mov_b32_e32 v61, 0
	v_mov_b32_e32 v62, 0
	v_mov_b32_e32 v63, 0
	v_mov_b32_e32 v64, 0
	v_mov_b32_e32 v65, 0
	v_mov_b32_e32 v66, 0
	v_mov_b32_e32 v67, 0
	v_mov_b32_e32 v68, 0
	v_mov_b32_e32 v69, 0
	v_mov_b32_e32 v70, 0
	v_mov_b32_e32 v71, 0
	v_mov_b32_e32 v72, 0
	v_mov_b32_e32 v73, 0
	v_mov_b32_e32 v74, 0
	v_mov_b32_e32 v75, 0
	v_mov_b32_e32 v76, 0
	v_mov_b32_e32 v77, 0
	v_mov_b32_e32 v78, 0
	v_mov_b32_e32 v79, 0
	v_mov_b32_e32 v80, 0
	v_mov_b32_e32 v81, 0
	v_mov_b32_e32 v82, 0
	v_mov_b32_e32 v83, 0
	v_mov_b32_e32 v84, 0
	v_mov_b32_e32 v85, 0
	v_mov_b32_e32 v86, 0
	v_mov_b32_e32 v87, 0
	v_mov_b32_e32 v88, 0
	v_mov_b32_e32 v89, 0
	v_mov_b32_e32 v90, 0
	v_mov_b32_e32 v91, 0
	v_mov_b32_e32 v92, 0
	v_mov_b32_e32 v93, 0
	v_mov_b32_e32 v94, 0
	v_mov_b32_e32 v95, 0
	v_mov_b32_e32 v96, 0
	v_mov_b32_e32 v97, 0
	v_mov_b32_e32 v98, 0
	v_mov_b32_e32 v99, 0
	s_mov_b32 s34, 0
	s_add_u32 s35, s35, s52
	s_cmp_ge_u32 s31, s30
	s_cbranch_scc1 .Lgm_wo_exit

.Lgm_wi_join:
	s_waitcnt lgkmcnt(13)
	v_mfma_f32_16x16x32_bf16 v[4:7], v[100:103], v[124:127], v[4:7]
	v_mfma_f32_16x16x32_bf16 v[20:23], v[104:107], v[124:127], v[20:23]
	v_mfma_f32_16x16x32_bf16 v[36:39], v[108:111], v[124:127], v[36:39]
	v_mfma_f32_16x16x32_bf16 v[52:55], v[112:115], v[124:127], v[52:55]
	v_mfma_f32_16x16x32_bf16 v[68:71], v[116:119], v[124:127], v[68:71]
	v_mfma_f32_16x16x32_bf16 v[84:87], v[120:123], v[124:127], v[84:87]
	s_waitcnt lgkmcnt(12)
	v_mfma_f32_16x16x32_bf16 v[8:11], v[100:103], v[128:131], v[8:11]
	v_mfma_f32_16x16x32_bf16 v[24:27], v[104:107], v[128:131], v[24:27]
	v_mfma_f32_16x16x32_bf16 v[40:43], v[108:111], v[128:131], v[40:43]
	v_mfma_f32_16x16x32_bf16 v[56:59], v[112:115], v[128:131], v[56:59]
	v_mfma_f32_16x16x32_bf16 v[72:75], v[116:119], v[128:131], v[72:75]
	v_mfma_f32_16x16x32_bf16 v[88:91], v[120:123], v[128:131], v[88:91]
	s_waitcnt lgkmcnt(11)
	v_mfma_f32_16x16x32_bf16 v[12:15], v[100:103], v[132:135], v[12:15]
	v_mfma_f32_16x16x32_bf16 v[28:31], v[104:107], v[132:135], v[28:31]
	v_mfma_f32_16x16x32_bf16 v[44:47], v[108:111], v[132:135], v[44:47]
	v_mfma_f32_16x16x32_bf16 v[60:63], v[112:115], v[132:135], v[60:63]
	v_mfma_f32_16x16x32_bf16 v[76:79], v[116:119], v[132:135], v[76:79]
	v_mfma_f32_16x16x32_bf16 v[92:95], v[120:123], v[132:135], v[92:95]
	s_waitcnt lgkmcnt(10)
	v_mfma_f32_16x16x32_bf16 v[16:19], v[100:103], v[136:139], v[16:19]
	v_mfma_f32_16x16x32_bf16 v[32:35], v[104:107], v[136:139], v[32:35]
	v_mfma_f32_16x16x32_bf16 v[48:51], v[108:111], v[136:139], v[48:51]
	v_mfma_f32_16x16x32_bf16 v[64:67], v[112:115], v[136:139], v[64:67]
	v_mfma_f32_16x16x32_bf16 v[80:83], v[116:119], v[136:139], v[80:83]
	v_mfma_f32_16x16x32_bf16 v[96:99], v[120:123], v[136:139], v[96:99]
	s_waitcnt lgkmcnt(0)
	s_add_u32 s34, s34, 1
	s_add_u32 s31, s31, 1
	s_cmp_lt_u32 s34, 16
	s_cbranch_scc1 .Lgm_wi_rot
	v_mfma_f32_16x16x32_bf16 v[4:7], v[140:143], v[164:167], v[4:7]
	v_mfma_f32_16x16x32_bf16 v[20:23], v[144:147], v[164:167], v[20:23]
	v_mfma_f32_16x16x32_bf16 v[36:39], v[148:151], v[164:167], v[36:39]
	v_mfma_f32_16x16x32_bf16 v[52:55], v[152:155], v[164:167], v[52:55]
	v_mfma_f32_16x16x32_bf16 v[68:71], v[156:159], v[164:167], v[68:71]
	v_mfma_f32_16x16x32_bf16 v[84:87], v[160:163], v[164:167], v[84:87]
	v_mfma_f32_16x16x32_bf16 v[8:11], v[140:143], v[168:171], v[8:11]
	v_mfma_f32_16x16x32_bf16 v[24:27], v[144:147], v[168:171], v[24:27]
	v_mfma_f32_16x16x32_bf16 v[40:43], v[148:151], v[168:171], v[40:43]
	v_mfma_f32_16x16x32_bf16 v[56:59], v[152:155], v[168:171], v[56:59]
	v_mfma_f32_16x16x32_bf16 v[72:75], v[156:159], v[168:171], v[72:75]
	v_mfma_f32_16x16x32_bf16 v[88:91], v[160:163], v[168:171], v[88:91]
	v_mfma_f32_16x16x32_bf16 v[12:15], v[140:143], v[172:175], v[12:15]
	v_mfma_f32_16x16x32_bf16 v[28:31], v[144:147], v[172:175], v[28:31]
	v_mfma_f32_16x16x32_bf16 v[44:47], v[148:151], v[172:175], v[44:47]
	v_mfma_f32_16x16x32_bf16 v[60:63], v[152:155], v[172:175], v[60:63]
	v_mfma_f32_16x16x32_bf16 v[76:79], v[156:159], v[172:175], v[76:79]
	v_mfma_f32_16x16x32_bf16 v[92:95], v[160:163], v[172:175], v[92:95]
	v_mfma_f32_16x16x32_bf16 v[16:19], v[140:143], v[176:179], v[16:19]
	v_mfma_f32_16x16x32_bf16 v[32:35], v[144:147], v[176:179], v[32:35]
	v_mfma_f32_16x16x32_bf16 v[48:51], v[148:151], v[176:179], v[48:51]
	v_mfma_f32_16x16x32_bf16 v[64:67], v[152:155], v[176:179], v[64:67]
	v_mfma_f32_16x16x32_bf16 v[80:83], v[156:159], v[176:179], v[80:83]
	v_mfma_f32_16x16x32_bf16 v[96:99], v[160:163], v[176:179], v[96:99]
	s_and_b32 s6, s35, 31
	s_lshr_b32 s7, s35, 5
	s_mul_i32 s6, s6, 192
	s_lshl_b32 s7, s7, 7
	s_nop 7
	s_mul_i32 s4, s6, 0x2440
	s_lshl_b32 s5, s7, 2
	s_add_u32 s4, s4, s5
	v_add_u32_e32 v197, s4, v205
	v_add_u32_e32 v192, s7, v193
	s_mov_b32 s4, 0x910
	v_cmp_gt_u32_e32 vcc, s4, v192
	s_mov_b64 s[4:5], exec
	ds_write_b32 v203, v4 offset:0
	ds_write_b32 v203, v5 offset:272
	ds_write_b32 v203, v6 offset:544
	ds_write_b32 v203, v7 offset:816
	ds_write_b32 v203, v8 offset:64
	ds_write_b32 v203, v9 offset:336
	ds_write_b32 v203, v10 offset:608
	ds_write_b32 v203, v11 offset:880
	ds_write_b32 v203, v12 offset:128
	ds_write_b32 v203, v13 offset:400
	ds_write_b32 v203, v14 offset:672
	ds_write_b32 v203, v15 offset:944
	ds_write_b32 v203, v16 offset:192
	ds_write_b32 v203, v17 offset:464
	ds_write_b32 v203, v18 offset:736
	ds_write_b32 v203, v19 offset:1008
	s_waitcnt lgkmcnt(0)
	ds_read_b128 v[156:159], v204 offset:0
	ds_read_b128 v[160:163], v204 offset:1088
	ds_read_b128 v[164:167], v204 offset:2176
	ds_read_b128 v[168:171], v204 offset:3264
	s_waitcnt lgkmcnt(0)
	s_and_b64 exec, s[4:5], vcc
	global_store_dwordx4 v197, v[156:159], s[56:57]
	v_add_u32_e32 v197, 0x9100, v197
	global_store_dwordx4 v197, v[160:163], s[56:57]
	v_add_u32_e32 v197, 0x9100, v197
	global_store_dwordx4 v197, v[164:167], s[56:57]
	v_add_u32_e32 v197, 0x9100, v197
	global_store_dwordx4 v197, v[168:171], s[56:57]
	v_add_u32_e32 v197, 0x9100, v197
	s_mov_b64 exec, s[4:5]
	s_nop 1
	ds_write_b32 v203, v20 offset:0
	ds_write_b32 v203, v21 offset:272
	ds_write_b32 v203, v22 offset:544
	ds_write_b32 v203, v23 offset:816
	ds_write_b32 v203, v24 offset:64
	ds_write_b32 v203, v25 offset:336
	ds_write_b32 v203, v26 offset:608
	ds_write_b32 v203, v27 offset:880
	ds_write_b32 v203, v28 offset:128
	ds_write_b32 v203, v29 offset:400
	ds_write_b32 v203, v30 offset:672
	ds_write_b32 v203, v31 offset:944
	ds_write_b32 v203, v32 offset:192
	ds_write_b32 v203, v33 offset:464
	ds_write_b32 v203, v34 offset:736
	ds_write_b32 v203, v35 offset:1008
	s_waitcnt lgkmcnt(0)
	ds_read_b128 v[156:159], v204 offset:0
	ds_read_b128 v[160:163], v204 offset:1088
	ds_read_b128 v[164:167], v204 offset:2176
	ds_read_b128 v[168:171], v204 offset:3264
	s_waitcnt lgkmcnt(0)
	s_and_b64 exec, s[4:5], vcc
	global_store_dwordx4 v197, v[156:159], s[56:57]
	v_add_u32_e32 v197, 0x9100, v197
	global_store_dwordx4 v197, v[160:163], s[56:57]
	v_add_u32_e32 v197, 0x9100, v197
	global_store_dwordx4 v197, v[164:167], s[56:57]
	v_add_u32_e32 v197, 0x9100, v197
	global_store_dwordx4 v197, v[168:171], s[56:57]
	v_add_u32_e32 v197, 0x9100, v197
	s_mov_b64 exec, s[4:5]
	s_nop 1
	ds_write_b32 v203, v36 offset:0
	ds_write_b32 v203, v37 offset:272
	ds_write_b32 v203, v38 offset:544
	ds_write_b32 v203, v39 offset:816
	ds_write_b32 v203, v40 offset:64
	ds_write_b32 v203, v41 offset:336
	ds_write_b32 v203, v42 offset:608
	ds_write_b32 v203, v43 offset:880
	ds_write_b32 v203, v44 offset:128
	ds_write_b32 v203, v45 offset:400
	ds_write_b32 v203, v46 offset:672
	ds_write_b32 v203, v47 offset:944
	ds_write_b32 v203, v48 offset:192
	ds_write_b32 v203, v49 offset:464
	ds_write_b32 v203, v50 offset:736
	ds_write_b32 v203, v51 offset:1008
	s_waitcnt lgkmcnt(0)
	ds_read_b128 v[156:159], v204 offset:0
	ds_read_b128 v[160:163], v204 offset:1088
	ds_read_b128 v[164:167], v204 offset:2176
	ds_read_b128 v[168:171], v204 offset:3264
	s_waitcnt lgkmcnt(0)
	s_and_b64 exec, s[4:5], vcc
	global_store_dwordx4 v197, v[156:159], s[56:57]
	v_add_u32_e32 v197, 0x9100, v197
	global_store_dwordx4 v197, v[160:163], s[56:57]
	v_add_u32_e32 v197, 0x9100, v197
	global_store_dwordx4 v197, v[164:167], s[56:57]
	v_add_u32_e32 v197, 0x9100, v197
	global_store_dwordx4 v197, v[168:171], s[56:57]
	v_add_u32_e32 v197, 0x9100, v197
	s_mov_b64 exec, s[4:5]
	s_nop 1
	ds_write_b32 v203, v52 offset:0
	ds_write_b32 v203, v53 offset:272
	ds_write_b32 v203, v54 offset:544
	ds_write_b32 v203, v55 offset:816
	ds_write_b32 v203, v56 offset:64
	ds_write_b32 v203, v57 offset:336
	ds_write_b32 v203, v58 offset:608
	ds_write_b32 v203, v59 offset:880
	ds_write_b32 v203, v60 offset:128
	ds_write_b32 v203, v61 offset:400
	ds_write_b32 v203, v62 offset:672
	ds_write_b32 v203, v63 offset:944
	ds_write_b32 v203, v64 offset:192
	ds_write_b32 v203, v65 offset:464
	ds_write_b32 v203, v66 offset:736
	ds_write_b32 v203, v67 offset:1008
	s_waitcnt lgkmcnt(0)
	ds_read_b128 v[156:159], v204 offset:0
	ds_read_b128 v[160:163], v204 offset:1088
	ds_read_b128 v[164:167], v204 offset:2176
	ds_read_b128 v[168:171], v204 offset:3264
	s_waitcnt lgkmcnt(0)
	s_and_b64 exec, s[4:5], vcc
	global_store_dwordx4 v197, v[156:159], s[56:57]
	v_add_u32_e32 v197, 0x9100, v197
	global_store_dwordx4 v197, v[160:163], s[56:57]
	v_add_u32_e32 v197, 0x9100, v197
	global_store_dwordx4 v197, v[164:167], s[56:57]
	v_add_u32_e32 v197, 0x9100, v197
	global_store_dwordx4 v197, v[168:171], s[56:57]
	v_add_u32_e32 v197, 0x9100, v197
	s_mov_b64 exec, s[4:5]
	s_nop 1
	ds_write_b32 v203, v68 offset:0
	ds_write_b32 v203, v69 offset:272
	ds_write_b32 v203, v70 offset:544
	ds_write_b32 v203, v71 offset:816
	ds_write_b32 v203, v72 offset:64
	ds_write_b32 v203, v73 offset:336
	ds_write_b32 v203, v74 offset:608
	ds_write_b32 v203, v75 offset:880
	ds_write_b32 v203, v76 offset:128
	ds_write_b32 v203, v77 offset:400
	ds_write_b32 v203, v78 offset:672
	ds_write_b32 v203, v79 offset:944
	ds_write_b32 v203, v80 offset:192
	ds_write_b32 v203, v81 offset:464
	ds_write_b32 v203, v82 offset:736
	ds_write_b32 v203, v83 offset:1008
	s_waitcnt lgkmcnt(0)
	ds_read_b128 v[156:159], v204 offset:0
	ds_read_b128 v[160:163], v204 offset:1088
	ds_read_b128 v[164:167], v204 offset:2176
	ds_read_b128 v[168:171], v204 offset:3264
	s_waitcnt lgkmcnt(0)
	s_and_b64 exec, s[4:5], vcc
	global_store_dwordx4 v197, v[156:159], s[56:57]
	v_add_u32_e32 v197, 0x9100, v197
	global_store_dwordx4 v197, v[160:163], s[56:57]
	v_add_u32_e32 v197, 0x9100, v197
	global_store_dwordx4 v197, v[164:167], s[56:57]
	v_add_u32_e32 v197, 0x9100, v197
	global_store_dwordx4 v197, v[168:171], s[56:57]
	v_add_u32_e32 v197, 0x9100, v197
	s_mov_b64 exec, s[4:5]
	s_nop 1
	ds_write_b32 v203, v84 offset:0
	ds_write_b32 v203, v85 offset:272
	ds_write_b32 v203, v86 offset:544
	ds_write_b32 v203, v87 offset:816
	ds_write_b32 v203, v88 offset:64
	ds_write_b32 v203, v89 offset:336
	ds_write_b32 v203, v90 offset:608
	ds_write_b32 v203, v91 offset:880
	ds_write_b32 v203, v92 offset:128
	ds_write_b32 v203, v93 offset:400
	ds_write_b32 v203, v94 offset:672
	ds_write_b32 v203, v95 offset:944
	ds_write_b32 v203, v96 offset:192
	ds_write_b32 v203, v97 offset:464
	ds_write_b32 v203, v98 offset:736
	ds_write_b32 v203, v99 offset:1008
	s_waitcnt lgkmcnt(0)
	ds_read_b128 v[156:159], v204 offset:0
	ds_read_b128 v[160:163], v204 offset:1088
	ds_read_b128 v[164:167], v204 offset:2176
	ds_read_b128 v[168:171], v204 offset:3264
	s_waitcnt lgkmcnt(0)
	s_and_b64 exec, s[4:5], vcc
	global_store_dwordx4 v197, v[156:159], s[56:57]
	v_add_u32_e32 v197, 0x9100, v197
	global_store_dwordx4 v197, v[160:163], s[56:57]
	v_add_u32_e32 v197, 0x9100, v197
	global_store_dwordx4 v197, v[164:167], s[56:57]
	v_add_u32_e32 v197, 0x9100, v197
	global_store_dwordx4 v197, v[168:171], s[56:57]
	v_add_u32_e32 v197, 0x9100, v197
	s_mov_b64 exec, s[4:5]
	s_nop 1
	v_mov_b32_e32 v4, 0
	v_mov_b32_e32 v5, 0
	v_mov_b32_e32 v6, 0
	v_mov_b32_e32 v7, 0
	v_mov_b32_e32 v8, 0
	v_mov_b32_e32 v9, 0
	v_mov_b32_e32 v10, 0
	v_mov_b32_e32 v11, 0
	v_mov_b32_e32 v12, 0
	v_mov_b32_e32 v13, 0
	v_mov_b32_e32 v14, 0
	v_mov_b32_e32 v15, 0
	v_mov_b32_e32 v16, 0
	v_mov_b32_e32 v17, 0
	v_mov_b32_e32 v18, 0
	v_mov_b32_e32 v19, 0
	v_mov_b32_e32 v20, 0
	v_mov_b32_e32 v21, 0
	v_mov_b32_e32 v22, 0
	v_mov_b32_e32 v23, 0
	v_mov_b32_e32 v24, 0
	v_mov_b32_e32 v25, 0
	v_mov_b32_e32 v26, 0
	v_mov_b32_e32 v27, 0
	v_mov_b32_e32 v28, 0
	v_mov_b32_e32 v29, 0
	v_mov_b32_e32 v30, 0
	v_mov_b32_e32 v31, 0
	v_mov_b32_e32 v32, 0
	v_mov_b32_e32 v33, 0
	v_mov_b32_e32 v34, 0
	v_mov_b32_e32 v35, 0
	v_mov_b32_e32 v36, 0
	v_mov_b32_e32 v37, 0
	v_mov_b32_e32 v38, 0
	v_mov_b32_e32 v39, 0
	v_mov_b32_e32 v40, 0
	v_mov_b32_e32 v41, 0
	v_mov_b32_e32 v42, 0
	v_mov_b32_e32 v43, 0
	v_mov_b32_e32 v44, 0
	v_mov_b32_e32 v45, 0
	v_mov_b32_e32 v46, 0
	v_mov_b32_e32 v47, 0
	v_mov_b32_e32 v48, 0
	v_mov_b32_e32 v49, 0
	v_mov_b32_e32 v50, 0
	v_mov_b32_e32 v51, 0
	v_mov_b32_e32 v52, 0
	v_mov_b32_e32 v53, 0
	v_mov_b32_e32 v54, 0
	v_mov_b32_e32 v55, 0
	v_mov_b32_e32 v56, 0
	v_mov_b32_e32 v57, 0
	v_mov_b32_e32 v58, 0
	v_mov_b32_e32 v59, 0
	v_mov_b32_e32 v60, 0
	v_mov_b32_e32 v61, 0
	v_mov_b32_e32 v62, 0
	v_mov_b32_e32 v63, 0
	v_mov_b32_e32 v64, 0
	v_mov_b32_e32 v65, 0
	v_mov_b32_e32 v66, 0
	v_mov_b32_e32 v67, 0
	v_mov_b32_e32 v68, 0
	v_mov_b32_e32 v69, 0
	v_mov_b32_e32 v70, 0
	v_mov_b32_e32 v71, 0
	v_mov_b32_e32 v72, 0
	v_mov_b32_e32 v73, 0
	v_mov_b32_e32 v74, 0
	v_mov_b32_e32 v75, 0
	v_mov_b32_e32 v76, 0
	v_mov_b32_e32 v77, 0
	v_mov_b32_e32 v78, 0
	v_mov_b32_e32 v79, 0
	v_mov_b32_e32 v80, 0
	v_mov_b32_e32 v81, 0
	v_mov_b32_e32 v82, 0
	v_mov_b32_e32 v83, 0
	v_mov_b32_e32 v84, 0
	v_mov_b32_e32 v85, 0
	v_mov_b32_e32 v86, 0
	v_mov_b32_e32 v87, 0
	v_mov_b32_e32 v88, 0
	v_mov_b32_e32 v89, 0
	v_mov_b32_e32 v90, 0
	v_mov_b32_e32 v91, 0
	v_mov_b32_e32 v92, 0
	v_mov_b32_e32 v93, 0
	v_mov_b32_e32 v94, 0
	v_mov_b32_e32 v95, 0
	v_mov_b32_e32 v96, 0
	v_mov_b32_e32 v97, 0
	v_mov_b32_e32 v98, 0
	v_mov_b32_e32 v99, 0
	s_mov_b32 s34, 0
	s_add_u32 s35, s35, s52
	s_cmp_ge_u32 s31, s30
	s_cbranch_scc1 .Lgm_wi_exit

.Lgm_glu_glu_ep4:
	ds_write_b32 v203, v4 offset:0
	ds_write_b32 v203, v5 offset:272
	ds_write_b32 v203, v6 offset:544
	ds_write_b32 v203, v7 offset:816
	ds_write_b32 v203, v8 offset:64
	ds_write_b32 v203, v9 offset:336
	ds_write_b32 v203, v10 offset:608
	ds_write_b32 v203, v11 offset:880
	ds_write_b32 v203, v12 offset:128
	ds_write_b32 v203, v13 offset:400
	ds_write_b32 v203, v14 offset:672
	ds_write_b32 v203, v15 offset:944
	ds_write_b32 v203, v16 offset:192
	ds_write_b32 v203, v17 offset:464
	ds_write_b32 v203, v18 offset:736
	ds_write_b32 v203, v19 offset:1008
	s_waitcnt lgkmcnt(0)
	ds_read_b128 v[156:159], v204 offset:0
	ds_read_b128 v[160:163], v204 offset:1088
	ds_read_b128 v[164:167], v204 offset:2176
	ds_read_b128 v[168:171], v204 offset:3264
	s_waitcnt vmcnt(23)
	s_waitcnt lgkmcnt(3)
	v_add_f32_e32 v156, v156, v148
	v_add_f32_e32 v157, v157, v149
	v_add_f32_e32 v158, v158, v150
	v_add_f32_e32 v159, v159, v151
	v_mul_f32_e32 v156, 0xbfb8aa3b, v156
	v_mul_f32_e32 v157, 0xbfb8aa3b, v157
	v_mul_f32_e32 v158, 0xbfb8aa3b, v158
	v_mul_f32_e32 v159, 0xbfb8aa3b, v159
	v_exp_f32_e32 v156, v156
	v_exp_f32_e32 v157, v157
	v_exp_f32_e32 v158, v158
	v_exp_f32_e32 v159, v159
	v_lshlrev_b32_e32 v172, 16, v100
	v_and_b32_e32 v173, s28, v100
	v_lshlrev_b32_e32 v174, 16, v101
	v_and_b32_e32 v175, s28, v101
	v_add_f32_e32 v156, 1.0, v156
	v_add_f32_e32 v157, 1.0, v157
	v_add_f32_e32 v158, 1.0, v158
	v_add_f32_e32 v159, 1.0, v159
	v_div_scale_f32 v0, vcc, v156, v156, 1.0
	v_rcp_f32_e32 v1, v0
	s_nop 0
	v_fma_f32 v3, -v0, v1, 1.0
	v_fmac_f32_e32 v1, v3, v1
	v_div_scale_f32 v3, vcc, 1.0, v156, 1.0
	v_mul_f32_e32 v152, v3, v1
	v_fma_f32 v153, -v0, v152, v3
	v_fmac_f32_e32 v152, v153, v1
	v_fma_f32 v0, -v0, v152, v3
	v_div_fmas_f32 v0, v0, v1, v152
	v_div_fixup_f32 v156, v0, v156, 1.0
	v_mul_f32_e32 v156, v156, v172
	v_div_scale_f32 v0, vcc, v157, v157, 1.0
	v_rcp_f32_e32 v1, v0
	s_nop 0
	v_fma_f32 v3, -v0, v1, 1.0
	v_fmac_f32_e32 v1, v3, v1
	v_div_scale_f32 v3, vcc, 1.0, v157, 1.0
	v_mul_f32_e32 v152, v3, v1
	v_fma_f32 v153, -v0, v152, v3
	v_fmac_f32_e32 v152, v153, v1
	v_fma_f32 v0, -v0, v152, v3
	v_div_fmas_f32 v0, v0, v1, v152
	v_div_fixup_f32 v157, v0, v157, 1.0
	v_mul_f32_e32 v157, v157, v173
	v_div_scale_f32 v0, vcc, v158, v158, 1.0
	v_rcp_f32_e32 v1, v0
	s_nop 0
	v_fma_f32 v3, -v0, v1, 1.0
	v_fmac_f32_e32 v1, v3, v1
	v_div_scale_f32 v3, vcc, 1.0, v158, 1.0
	v_mul_f32_e32 v152, v3, v1
	v_fma_f32 v153, -v0, v152, v3
	v_fmac_f32_e32 v152, v153, v1
	v_fma_f32 v0, -v0, v152, v3
	v_div_fmas_f32 v0, v0, v1, v152
	v_div_fixup_f32 v158, v0, v158, 1.0
	v_mul_f32_e32 v158, v158, v174
	v_div_scale_f32 v0, vcc, v159, v159, 1.0
	v_rcp_f32_e32 v1, v0
	s_nop 0
	v_fma_f32 v3, -v0, v1, 1.0
	v_fmac_f32_e32 v1, v3, v1
	v_div_scale_f32 v3, vcc, 1.0, v159, 1.0
	v_mul_f32_e32 v152, v3, v1
	v_fma_f32 v153, -v0, v152, v3
	v_fmac_f32_e32 v152, v153, v1
	v_fma_f32 v0, -v0, v152, v3
	v_div_fmas_f32 v0, v0, v1, v152
	v_div_fixup_f32 v159, v0, v159, 1.0
	v_mul_f32_e32 v159, v159, v175
	v_cvt_pk_bf16_f32 v176, v156, v157
	v_cvt_pk_bf16_f32 v177, v158, v159
	global_store_dwordx2 v197, v[176:177], s[56:57]
	v_add_u32_e32 v197, 0x2000, v197
	s_waitcnt vmcnt(23)
	s_waitcnt lgkmcnt(2)
	v_add_f32_e32 v160, v160, v148
	v_add_f32_e32 v161, v161, v149
	v_add_f32_e32 v162, v162, v150
	v_add_f32_e32 v163, v163, v151
	v_mul_f32_e32 v160, 0xbfb8aa3b, v160
	v_mul_f32_e32 v161, 0xbfb8aa3b, v161
	v_mul_f32_e32 v162, 0xbfb8aa3b, v162
	v_mul_f32_e32 v163, 0xbfb8aa3b, v163
	v_exp_f32_e32 v160, v160
	v_exp_f32_e32 v161, v161
	v_exp_f32_e32 v162, v162
	v_exp_f32_e32 v163, v163
	v_lshlrev_b32_e32 v172, 16, v102
	v_and_b32_e32 v173, s28, v102
	v_lshlrev_b32_e32 v174, 16, v103
	v_and_b32_e32 v175, s28, v103
	v_add_f32_e32 v160, 1.0, v160
	v_add_f32_e32 v161, 1.0, v161
	v_add_f32_e32 v162, 1.0, v162
	v_add_f32_e32 v163, 1.0, v163
	v_div_scale_f32 v0, vcc, v160, v160, 1.0
	v_rcp_f32_e32 v1, v0
	s_nop 0
	v_fma_f32 v3, -v0, v1, 1.0
	v_fmac_f32_e32 v1, v3, v1
	v_div_scale_f32 v3, vcc, 1.0, v160, 1.0
	v_mul_f32_e32 v152, v3, v1
	v_fma_f32 v153, -v0, v152, v3
	v_fmac_f32_e32 v152, v153, v1
	v_fma_f32 v0, -v0, v152, v3
	v_div_fmas_f32 v0, v0, v1, v152
	v_div_fixup_f32 v160, v0, v160, 1.0
	v_mul_f32_e32 v160, v160, v172
	v_div_scale_f32 v0, vcc, v161, v161, 1.0
	v_rcp_f32_e32 v1, v0
	s_nop 0
	v_fma_f32 v3, -v0, v1, 1.0
	v_fmac_f32_e32 v1, v3, v1
	v_div_scale_f32 v3, vcc, 1.0, v161, 1.0
	v_mul_f32_e32 v152, v3, v1
	v_fma_f32 v153, -v0, v152, v3
	v_fmac_f32_e32 v152, v153, v1
	v_fma_f32 v0, -v0, v152, v3
	v_div_fmas_f32 v0, v0, v1, v152
	v_div_fixup_f32 v161, v0, v161, 1.0
	v_mul_f32_e32 v161, v161, v173
	v_div_scale_f32 v0, vcc, v162, v162, 1.0
	v_rcp_f32_e32 v1, v0
	s_nop 0
	v_fma_f32 v3, -v0, v1, 1.0
	v_fmac_f32_e32 v1, v3, v1
	v_div_scale_f32 v3, vcc, 1.0, v162, 1.0
	v_mul_f32_e32 v152, v3, v1
	v_fma_f32 v153, -v0, v152, v3
	v_fmac_f32_e32 v152, v153, v1
	v_fma_f32 v0, -v0, v152, v3
	v_div_fmas_f32 v0, v0, v1, v152
	v_div_fixup_f32 v162, v0, v162, 1.0
	v_mul_f32_e32 v162, v162, v174
	v_div_scale_f32 v0, vcc, v163, v163, 1.0
	v_rcp_f32_e32 v1, v0
	s_nop 0
	v_fma_f32 v3, -v0, v1, 1.0
	v_fmac_f32_e32 v1, v3, v1
	v_div_scale_f32 v3, vcc, 1.0, v163, 1.0
	v_mul_f32_e32 v152, v3, v1
	v_fma_f32 v153, -v0, v152, v3
	v_fmac_f32_e32 v152, v153, v1
	v_fma_f32 v0, -v0, v152, v3
	v_div_fmas_f32 v0, v0, v1, v152
	v_div_fixup_f32 v163, v0, v163, 1.0
	v_mul_f32_e32 v163, v163, v175
	v_cvt_pk_bf16_f32 v178, v160, v161
	v_cvt_pk_bf16_f32 v179, v162, v163
	global_store_dwordx2 v197, v[178:179], s[56:57]
	v_add_u32_e32 v197, 0x2000, v197
	s_waitcnt vmcnt(23)
	s_waitcnt lgkmcnt(1)
	v_add_f32_e32 v164, v164, v148
	v_add_f32_e32 v165, v165, v149
	v_add_f32_e32 v166, v166, v150
	v_add_f32_e32 v167, v167, v151
	v_mul_f32_e32 v164, 0xbfb8aa3b, v164
	v_mul_f32_e32 v165, 0xbfb8aa3b, v165
	v_mul_f32_e32 v166, 0xbfb8aa3b, v166
	v_mul_f32_e32 v167, 0xbfb8aa3b, v167
	v_exp_f32_e32 v164, v164
	v_exp_f32_e32 v165, v165
	v_exp_f32_e32 v166, v166
	v_exp_f32_e32 v167, v167
	v_lshlrev_b32_e32 v172, 16, v104
	v_and_b32_e32 v173, s28, v104
	v_lshlrev_b32_e32 v174, 16, v105
	v_and_b32_e32 v175, s28, v105
	v_add_f32_e32 v164, 1.0, v164
	v_add_f32_e32 v165, 1.0, v165
	v_add_f32_e32 v166, 1.0, v166
	v_add_f32_e32 v167, 1.0, v167
	v_div_scale_f32 v0, vcc, v164, v164, 1.0
	v_rcp_f32_e32 v1, v0
	s_nop 0
	v_fma_f32 v3, -v0, v1, 1.0
	v_fmac_f32_e32 v1, v3, v1
	v_div_scale_f32 v3, vcc, 1.0, v164, 1.0
	v_mul_f32_e32 v152, v3, v1
	v_fma_f32 v153, -v0, v152, v3
	v_fmac_f32_e32 v152, v153, v1
	v_fma_f32 v0, -v0, v152, v3
	v_div_fmas_f32 v0, v0, v1, v152
	v_div_fixup_f32 v164, v0, v164, 1.0
	v_mul_f32_e32 v164, v164, v172
	v_div_scale_f32 v0, vcc, v165, v165, 1.0
	v_rcp_f32_e32 v1, v0
	s_nop 0
	v_fma_f32 v3, -v0, v1, 1.0
	v_fmac_f32_e32 v1, v3, v1
	v_div_scale_f32 v3, vcc, 1.0, v165, 1.0
	v_mul_f32_e32 v152, v3, v1
	v_fma_f32 v153, -v0, v152, v3
	v_fmac_f32_e32 v152, v153, v1
	v_fma_f32 v0, -v0, v152, v3
	v_div_fmas_f32 v0, v0, v1, v152
	v_div_fixup_f32 v165, v0, v165, 1.0
	v_mul_f32_e32 v165, v165, v173
	v_div_scale_f32 v0, vcc, v166, v166, 1.0
	v_rcp_f32_e32 v1, v0
	s_nop 0
	v_fma_f32 v3, -v0, v1, 1.0
	v_fmac_f32_e32 v1, v3, v1
	v_div_scale_f32 v3, vcc, 1.0, v166, 1.0
	v_mul_f32_e32 v152, v3, v1
	v_fma_f32 v153, -v0, v152, v3
	v_fmac_f32_e32 v152, v153, v1
	v_fma_f32 v0, -v0, v152, v3
	v_div_fmas_f32 v0, v0, v1, v152
	v_div_fixup_f32 v166, v0, v166, 1.0
	v_mul_f32_e32 v166, v166, v174
	v_div_scale_f32 v0, vcc, v167, v167, 1.0
	v_rcp_f32_e32 v1, v0
	s_nop 0
	v_fma_f32 v3, -v0, v1, 1.0
	v_fmac_f32_e32 v1, v3, v1
	v_div_scale_f32 v3, vcc, 1.0, v167, 1.0
	v_mul_f32_e32 v152, v3, v1
	v_fma_f32 v153, -v0, v152, v3
	v_fmac_f32_e32 v152, v153, v1
	v_fma_f32 v0, -v0, v152, v3
	v_div_fmas_f32 v0, v0, v1, v152
	v_div_fixup_f32 v167, v0, v167, 1.0
	v_mul_f32_e32 v167, v167, v175
	v_cvt_pk_bf16_f32 v176, v164, v165
	v_cvt_pk_bf16_f32 v177, v166, v167
	global_store_dwordx2 v197, v[176:177], s[56:57]
	v_add_u32_e32 v197, 0x2000, v197
	s_waitcnt vmcnt(23)
	s_waitcnt lgkmcnt(0)
	v_add_f32_e32 v168, v168, v148
	v_add_f32_e32 v169, v169, v149
	v_add_f32_e32 v170, v170, v150
	v_add_f32_e32 v171, v171, v151
	v_mul_f32_e32 v168, 0xbfb8aa3b, v168
	v_mul_f32_e32 v169, 0xbfb8aa3b, v169
	v_mul_f32_e32 v170, 0xbfb8aa3b, v170
	v_mul_f32_e32 v171, 0xbfb8aa3b, v171
	v_exp_f32_e32 v168, v168
	v_exp_f32_e32 v169, v169
	v_exp_f32_e32 v170, v170
	v_exp_f32_e32 v171, v171
	v_lshlrev_b32_e32 v172, 16, v106
	v_and_b32_e32 v173, s28, v106
	v_lshlrev_b32_e32 v174, 16, v107
	v_and_b32_e32 v175, s28, v107
	v_add_f32_e32 v168, 1.0, v168
	v_add_f32_e32 v169, 1.0, v169
	v_add_f32_e32 v170, 1.0, v170
	v_add_f32_e32 v171, 1.0, v171
	v_div_scale_f32 v0, vcc, v168, v168, 1.0
	v_rcp_f32_e32 v1, v0
	s_nop 0
	v_fma_f32 v3, -v0, v1, 1.0
	v_fmac_f32_e32 v1, v3, v1
	v_div_scale_f32 v3, vcc, 1.0, v168, 1.0
	v_mul_f32_e32 v152, v3, v1
	v_fma_f32 v153, -v0, v152, v3
	v_fmac_f32_e32 v152, v153, v1
	v_fma_f32 v0, -v0, v152, v3
	v_div_fmas_f32 v0, v0, v1, v152
	v_div_fixup_f32 v168, v0, v168, 1.0
	v_mul_f32_e32 v168, v168, v172
	v_div_scale_f32 v0, vcc, v169, v169, 1.0
	v_rcp_f32_e32 v1, v0
	s_nop 0
	v_fma_f32 v3, -v0, v1, 1.0
	v_fmac_f32_e32 v1, v3, v1
	v_div_scale_f32 v3, vcc, 1.0, v169, 1.0
	v_mul_f32_e32 v152, v3, v1
	v_fma_f32 v153, -v0, v152, v3
	v_fmac_f32_e32 v152, v153, v1
	v_fma_f32 v0, -v0, v152, v3
	v_div_fmas_f32 v0, v0, v1, v152
	v_div_fixup_f32 v169, v0, v169, 1.0
	v_mul_f32_e32 v169, v169, v173
	v_div_scale_f32 v0, vcc, v170, v170, 1.0
	v_rcp_f32_e32 v1, v0
	s_nop 0
	v_fma_f32 v3, -v0, v1, 1.0
	v_fmac_f32_e32 v1, v3, v1
	v_div_scale_f32 v3, vcc, 1.0, v170, 1.0
	v_mul_f32_e32 v152, v3, v1
	v_fma_f32 v153, -v0, v152, v3
	v_fmac_f32_e32 v152, v153, v1
	v_fma_f32 v0, -v0, v152, v3
	v_div_fmas_f32 v0, v0, v1, v152
	v_div_fixup_f32 v170, v0, v170, 1.0
	v_mul_f32_e32 v170, v170, v174
	v_div_scale_f32 v0, vcc, v171, v171, 1.0
	v_rcp_f32_e32 v1, v0
	s_nop 0
	v_fma_f32 v3, -v0, v1, 1.0
	v_fmac_f32_e32 v1, v3, v1
	v_div_scale_f32 v3, vcc, 1.0, v171, 1.0
	v_mul_f32_e32 v152, v3, v1
	v_fma_f32 v153, -v0, v152, v3
	v_fmac_f32_e32 v152, v153, v1
	v_fma_f32 v0, -v0, v152, v3
	v_div_fmas_f32 v0, v0, v1, v152
	v_div_fixup_f32 v171, v0, v171, 1.0
	v_mul_f32_e32 v171, v171, v175
	v_cvt_pk_bf16_f32 v178, v168, v169
	v_cvt_pk_bf16_f32 v179, v170, v171
	global_store_dwordx2 v197, v[178:179], s[56:57]
	v_add_u32_e32 v197, 0x2000, v197
	s_add_u32 s4, s4, 1
	s_cmp_eq_u32 s4, 6
	s_cbranch_scc1 .Lgm_glu_glu_done5
	s_waitcnt vmcnt(4)
	v_mov_b32_e32 v4, v20
	v_mov_b32_e32 v5, v21
	v_mov_b32_e32 v6, v22
	v_mov_b32_e32 v7, v23
	v_mov_b32_e32 v8, v24
	v_mov_b32_e32 v9, v25
	v_mov_b32_e32 v10, v26
	v_mov_b32_e32 v11, v27
	v_mov_b32_e32 v12, v28
	v_mov_b32_e32 v13, v29
	v_mov_b32_e32 v14, v30
	v_mov_b32_e32 v15, v31
	v_mov_b32_e32 v16, v32
	v_mov_b32_e32 v17, v33
	v_mov_b32_e32 v18, v34
	v_mov_b32_e32 v19, v35
	v_mov_b32_e32 v20, v36
	v_mov_b32_e32 v21, v37
	v_mov_b32_e32 v22, v38
	v_mov_b32_e32 v23, v39
	v_mov_b32_e32 v24, v40
	v_mov_b32_e32 v25, v41
	v_mov_b32_e32 v26, v42
	v_mov_b32_e32 v27, v43
	v_mov_b32_e32 v28, v44
	v_mov_b32_e32 v29, v45
	v_mov_b32_e32 v30, v46
	v_mov_b32_e32 v31, v47
	v_mov_b32_e32 v32, v48
	v_mov_b32_e32 v33, v49
	v_mov_b32_e32 v34, v50
	v_mov_b32_e32 v35, v51
	v_mov_b32_e32 v36, v52
	v_mov_b32_e32 v37, v53
	v_mov_b32_e32 v38, v54
	v_mov_b32_e32 v39, v55
	v_mov_b32_e32 v40, v56
	v_mov_b32_e32 v41, v57
	v_mov_b32_e32 v42, v58
	v_mov_b32_e32 v43, v59
	v_mov_b32_e32 v44, v60
	v_mov_b32_e32 v45, v61
	v_mov_b32_e32 v46, v62
	v_mov_b32_e32 v47, v63
	v_mov_b32_e32 v48, v64
	v_mov_b32_e32 v49, v65
	v_mov_b32_e32 v50, v66
	v_mov_b32_e32 v51, v67
	v_mov_b32_e32 v52, v68
	v_mov_b32_e32 v53, v69
	v_mov_b32_e32 v54, v70
	v_mov_b32_e32 v55, v71
	v_mov_b32_e32 v56, v72
	v_mov_b32_e32 v57, v73
	v_mov_b32_e32 v58, v74
	v_mov_b32_e32 v59, v75
	v_mov_b32_e32 v60, v76
	v_mov_b32_e32 v61, v77
	v_mov_b32_e32 v62, v78
	v_mov_b32_e32 v63, v79
	v_mov_b32_e32 v64, v80
	v_mov_b32_e32 v65, v81
	v_mov_b32_e32 v66, v82
	v_mov_b32_e32 v67, v83
	v_mov_b32_e32 v68, v84
	v_mov_b32_e32 v69, v85
	v_mov_b32_e32 v70, v86
	v_mov_b32_e32 v71, v87
	v_mov_b32_e32 v72, v88
	v_mov_b32_e32 v73, v89
	v_mov_b32_e32 v74, v90
	v_mov_b32_e32 v75, v91
	v_mov_b32_e32 v76, v92
	v_mov_b32_e32 v77, v93
	v_mov_b32_e32 v78, v94
	v_mov_b32_e32 v79, v95
	v_mov_b32_e32 v80, v96
	v_mov_b32_e32 v81, v97
	v_mov_b32_e32 v82, v98
	v_mov_b32_e32 v83, v99
	v_mov_b32_e32 v100, v108
	v_mov_b32_e32 v101, v109
	v_mov_b32_e32 v102, v110
	v_mov_b32_e32 v103, v111
	v_mov_b32_e32 v104, v112
	v_mov_b32_e32 v105, v113
	v_mov_b32_e32 v106, v114
	v_mov_b32_e32 v107, v115
	v_mov_b32_e32 v108, v116
	v_mov_b32_e32 v109, v117
	v_mov_b32_e32 v110, v118
	v_mov_b32_e32 v111, v119
	v_mov_b32_e32 v112, v120
	v_mov_b32_e32 v113, v121
	v_mov_b32_e32 v114, v122
	v_mov_b32_e32 v115, v123
	v_mov_b32_e32 v116, v124
	v_mov_b32_e32 v117, v125
	v_mov_b32_e32 v118, v126
	v_mov_b32_e32 v119, v127
	v_mov_b32_e32 v120, v128
	v_mov_b32_e32 v121, v129
	v_mov_b32_e32 v122, v130
	v_mov_b32_e32 v123, v131
	v_mov_b32_e32 v124, v132
	v_mov_b32_e32 v125, v133
	v_mov_b32_e32 v126, v134
	v_mov_b32_e32 v127, v135
	v_mov_b32_e32 v128, v136
	v_mov_b32_e32 v129, v137
	v_mov_b32_e32 v130, v138
	v_mov_b32_e32 v131, v139
	v_mov_b32_e32 v132, v140
	v_mov_b32_e32 v133, v141
	v_mov_b32_e32 v134, v142
	v_mov_b32_e32 v135, v143
	v_mov_b32_e32 v136, v144
	v_mov_b32_e32 v137, v145
	v_mov_b32_e32 v138, v146
	v_mov_b32_e32 v139, v147
	s_branch .Lgm_glu_glu_ep4
